# attention: static s_setprio 1 for waves 4-7 during each pass (on top of wait fixes)
# speedup vs baseline: 1.0053x; 1.0053x over previous
.LBB0_509:
	s_xor_b64 s[18:19], s[4:5], -1
	s_lshl_b64 s[4:5], s[0:1], 1
	s_add_u32 s22, s56, s4
	s_addc_u32 s23, s57, s5
	v_mov_b32_e32 v2, v208
	s_add_u32 s0, s58, s4
	s_addc_u32 s1, s59, s5
	v_readfirstlane_b32 s20, v2
	s_ashr_i32 s24, s20, 6
	s_cmp_lt_u32 s24, 4
	s_cbranch_scc1 .Lprio1_skip
	s_setprio 1
.Lprio1_skip:
	s_and_b32 s20, s20, 0x3fffffc0
	s_lshl_b32 s20, s20, 2
	v_and_b32_e32 v219, 31, v2
	s_add_i32 s21, s20, 0
	s_lshl_b32 s20, s24, 5
	v_or_b32_e32 v0, s20, v219
	s_waitcnt lgkmcnt(0)
	v_ashrrev_i32_e32 v1, 31, v0
	v_bfe_u32 v218, v2, 5, 1
	v_lshlrev_b64 v[0:1], 11, v[0:1]
	v_lshl_add_u64 v[0:1], s[22:23], 0, v[0:1]
	v_lshlrev_b32_e32 v210, 4, v218
	v_lshl_add_u64 v[0:1], v[0:1], 0, v[210:211]
	global_load_dwordx4 v[160:163], v[0:1], off
	global_load_dwordx4 v[164:167], v[0:1], off offset:32
	global_load_dwordx4 v[168:171], v[0:1], off offset:64
	global_load_dwordx4 v[172:175], v[0:1], off offset:96
	global_load_dwordx4 v[176:179], v[0:1], off offset:128
	global_load_dwordx4 v[180:183], v[0:1], off offset:160
	global_load_dwordx4 v[184:187], v[0:1], off offset:192
	global_load_dwordx4 v[188:191], v[0:1], off offset:224
	s_lshl_b32 s22, s24, 3
	v_bfe_u32 v1, v2, 4, 2
	v_or_b32_e32 v0, s22, v1
	v_bitop3_b32 v4, v1, v2, 15 bitop3:0x78
	v_ashrrev_i32_e32 v1, 31, v0
	v_lshlrev_b64 v[212:213], 10, v[0:1]
	v_or_b32_e32 v0, 4, v0
	v_and_b32_e32 v3, 15, v2
	v_ashrrev_i32_e32 v1, 31, v0
	v_bitop3_b32 v3, v0, v3, 7 bitop3:0x6c
	v_lshlrev_b64 v[214:215], 10, v[0:1]
	v_bfe_u32 v0, v2, 2, 3
	v_bitop3_b32 v0, s22, -13, v0 bitop3:0xc8
	v_lshrrev_b32_e32 v1, 1, v2
	s_lshl_b32 s22, s24, 2
	v_and_b32_e32 v1, 8, v1
	s_and_b32 s22, s22, 4
	v_or3_b32 v0, v0, v1, s22
	s_add_i32 s21, s21, 0x24000
	v_ashrrev_i32_e32 v1, 31, v0
	v_lshlrev_b32_e32 v11, 3, v2
	s_lshl_b32 s22, s24, 11
	v_lshl_or_b32 v212, v4, 3, v212
	v_lshlrev_b64 v[216:217], 10, v[0:1]
	v_and_b32_e32 v0, 32, v2
	v_and_b32_e32 v1, 24, v11
	s_cmp_lg_u32 0, -1
	v_or3_b32 v216, v216, v1, v0
	v_lshlrev_b64 v[0:1], 1, v[212:213]
	s_cselect_b32 s23, 0, 0
	v_and_b32_e32 v10, 63, v2
	v_lshl_or_b32 v214, v3, 3, v214
	v_lshlrev_b32_e32 v12, 4, v2
	v_lshlrev_b32_e32 v13, 1, v2
	v_lshl_add_u64 v[2:3], s[0:1], 0, v[0:1]
	s_add_i32 s75, s22, s23
	s_mov_b32 s25, m0
	s_mov_b32 m0, s75
	s_nop 0
	global_load_lds_dwordx4 v[2:3], off
	s_mov_b32 m0, s25
	v_lshlrev_b64 v[2:3], 1, v[214:215]
	s_or_b32 s25, s22, 0x400
	v_lshl_add_u64 v[4:5], s[0:1], 0, v[2:3]
	s_add_i32 s77, s25, s23
	s_mov_b32 s84, m0
	s_mov_b32 m0, s77
	s_nop 0
	global_load_lds_dwordx4 v[4:5], off
	s_mov_b32 m0, s84
	s_lshl_b32 s24, s24, 12
	v_lshlrev_b64 v[4:5], 1, v[216:217]
	s_add_i32 s84, s23, 0xc000
	v_lshl_add_u64 v[6:7], s[14:15], 0, v[4:5]
	s_add_i32 s77, s24, s84
	s_mov_b32 s85, m0
	s_mov_b32 m0, s77
	s_nop 0
	global_load_lds_dwordx4 v[6:7], off
	s_mov_b32 m0, s85
	s_or_b32 s85, s24, 0x400
	s_add_i32 s86, s85, s84
	v_lshl_add_u64 v[8:9], v[6:7], 0, s[8:9]
	s_mov_b32 s87, m0
	s_mov_b32 m0, s86
	s_nop 0
	global_load_lds_dwordx4 v[8:9], off
	s_mov_b32 m0, s87
	s_or_b32 s86, s24, 0x800
	s_add_i32 s87, s86, s84
	v_lshl_add_u64 v[8:9], v[6:7], 0, s[10:11]
	s_mov_b32 s96, m0
	s_mov_b32 m0, s87
	s_nop 0
	global_load_lds_dwordx4 v[8:9], off
	s_mov_b32 m0, s96
	s_or_b32 s87, s24, 0xc00
	s_add_i32 s96, s87, s84
	s_add_u32 s0, s0, 0x20000
	v_lshl_add_u64 v[6:7], v[6:7], 0, s[12:13]
	s_mov_b32 s97, m0
	s_mov_b32 m0, s96
	s_nop 0
	global_load_lds_dwordx4 v[6:7], off
	s_mov_b32 m0, s97
	s_addc_u32 s1, s1, 0
	s_add_i32 s96, s23, 0x4000
	v_lshl_add_u64 v[0:1], s[0:1], 0, v[0:1]
	s_add_i32 s22, s22, s96
	s_mov_b32 s97, m0
	s_mov_b32 m0, s22
	s_nop 0
	global_load_lds_dwordx4 v[0:1], off
	s_mov_b32 m0, s97
	v_lshl_add_u64 v[0:1], s[0:1], 0, v[2:3]
	s_add_i32 s25, s25, s96
	s_mov_b32 s0, m0
	s_mov_b32 m0, s25
	s_nop 0
	global_load_lds_dwordx4 v[0:1], off
	s_mov_b32 m0, s0
	s_add_i32 s23, s23, 0x14000
	v_lshl_add_u64 v[0:1], s[16:17], 0, v[4:5]
	s_add_i32 s24, s24, s23
	s_mov_b32 s0, m0
	s_mov_b32 m0, s24
	s_nop 0
	global_load_lds_dwordx4 v[0:1], off
	s_mov_b32 m0, s0
	v_lshl_add_u64 v[2:3], v[0:1], 0, s[8:9]
	s_add_i32 s85, s85, s23
	s_mov_b32 s0, m0
	s_mov_b32 m0, s85
	s_nop 0
	global_load_lds_dwordx4 v[2:3], off
	s_mov_b32 m0, s0
	v_lshl_add_u64 v[2:3], v[0:1], 0, s[10:11]
	s_add_i32 s86, s86, s23
	s_mov_b32 s0, m0
	s_mov_b32 m0, s86
	s_nop 0
	global_load_lds_dwordx4 v[2:3], off
	s_mov_b32 m0, s0
	v_lshl_add_u64 v[0:1], v[0:1], 0, s[12:13]
	s_add_i32 s87, s87, s23
	s_mov_b32 s0, m0
	s_mov_b32 m0, s87
	s_nop 0
	global_load_lds_dwordx4 v[0:1], off
	s_mov_b32 m0, s0
	s_movk_i32 s0, 0x70
	v_and_b32_e32 v1, 0x70, v12
	v_bitop3_b32 v221, v210, v12, s0 bitop3:0x78
	s_movk_i32 s0, 0x60
	v_bitop3_b32 v224, v210, v1, s0 bitop3:0x36
	s_movk_i32 s0, 0x80
	v_and_b32_e32 v0, 0x118, v11
	v_bitop3_b32 v225, v210, v1, s0 bitop3:0x36
	s_movk_i32 s0, 0xa0
	v_and_b32_e32 v14, 0xc0, v12
	v_bitop3_b32 v227, v210, v1, s0 bitop3:0x36
	s_movk_i32 s0, 0xc0
	v_and_or_b32 v0, v13, 32, v0
	v_bitop3_b32 v228, v210, v1, s0 bitop3:0x36
	s_movk_i32 s0, 0xe0
	v_add3_u32 v230, v14, s84, v0
	v_mov_b32_e32 v14, v211
	v_mov_b32_e32 v15, v211
	v_bitop3_b32 v222, v210, v1, 32 bitop3:0x36
	v_bitop3_b32 v223, v210, v1, 64 bitop3:0x36
	v_bitop3_b32 v229, v210, v1, s0 bitop3:0x36
	v_cmp_gt_u32_e64 s[0:1], 32, v10
	s_add_u32 s84, s66, s4
	v_mov_b32_e32 v0, v211
	v_mov_b32_e32 v1, v211
	v_mov_b32_e32 v2, v211
	v_mov_b32_e32 v3, v211
	v_mov_b32_e32 v4, v211
	v_mov_b32_e32 v5, v211
	v_mov_b32_e32 v6, v211
	v_mov_b32_e32 v7, v211
	v_mov_b32_e32 v8, v211
	v_mov_b32_e32 v9, v211
	v_mov_b32_e32 v10, v211
	v_mov_b32_e32 v11, v211
	v_mov_b32_e32 v12, v211
	v_mov_b32_e32 v13, v211
	v_mov_b64_e32 v[126:127], v[14:15]
	v_mov_b64_e32 v[110:111], v[14:15]
	v_mov_b64_e32 v[94:95], v[14:15]
	v_mov_b64_e32 v[78:79], v[14:15]
	v_mov_b64_e32 v[62:63], v[14:15]
	v_mov_b64_e32 v[46:47], v[14:15]
	v_mov_b64_e32 v[30:31], v[14:15]
	s_mov_b32 s74, 2
	s_mov_b32 s76, 0
	v_lshlrev_b32_e32 v220, 8, v219
	v_lshl_add_u32 v226, v219, 2, s21
	s_addc_u32 s85, s67, s5
	v_mov_b32_e32 v232, 0
	v_mov_b32_e32 v231, 0xf149f2ca
	s_mov_b64 s[22:23], 0
	v_mov_b64_e32 v[124:125], v[12:13]
	v_mov_b64_e32 v[122:123], v[10:11]
	v_mov_b64_e32 v[120:121], v[8:9]
	v_mov_b64_e32 v[118:119], v[6:7]
	v_mov_b64_e32 v[116:117], v[4:5]
	v_mov_b64_e32 v[114:115], v[2:3]
	v_mov_b64_e32 v[112:113], v[0:1]
	v_mov_b64_e32 v[108:109], v[12:13]
	v_mov_b64_e32 v[106:107], v[10:11]
	v_mov_b64_e32 v[104:105], v[8:9]
	v_mov_b64_e32 v[102:103], v[6:7]
	v_mov_b64_e32 v[100:101], v[4:5]
	v_mov_b64_e32 v[98:99], v[2:3]
	v_mov_b64_e32 v[96:97], v[0:1]
	v_mov_b64_e32 v[92:93], v[12:13]
	v_mov_b64_e32 v[90:91], v[10:11]
	v_mov_b64_e32 v[88:89], v[8:9]
	v_mov_b64_e32 v[86:87], v[6:7]
	v_mov_b64_e32 v[84:85], v[4:5]
	v_mov_b64_e32 v[82:83], v[2:3]
	v_mov_b64_e32 v[80:81], v[0:1]
	v_mov_b64_e32 v[76:77], v[12:13]
	v_mov_b64_e32 v[74:75], v[10:11]
	v_mov_b64_e32 v[72:73], v[8:9]
	v_mov_b64_e32 v[70:71], v[6:7]
	v_mov_b64_e32 v[68:69], v[4:5]
	v_mov_b64_e32 v[66:67], v[2:3]
	v_mov_b64_e32 v[64:65], v[0:1]
	v_mov_b64_e32 v[60:61], v[12:13]
	v_mov_b64_e32 v[58:59], v[10:11]
	v_mov_b64_e32 v[56:57], v[8:9]
	v_mov_b64_e32 v[54:55], v[6:7]
	v_mov_b64_e32 v[52:53], v[4:5]
	v_mov_b64_e32 v[50:51], v[2:3]
	v_mov_b64_e32 v[48:49], v[0:1]
	v_mov_b64_e32 v[44:45], v[12:13]
	v_mov_b64_e32 v[42:43], v[10:11]
	v_mov_b64_e32 v[40:41], v[8:9]
	v_mov_b64_e32 v[38:39], v[6:7]
	v_mov_b64_e32 v[36:37], v[4:5]
	v_mov_b64_e32 v[34:35], v[2:3]
	v_mov_b64_e32 v[32:33], v[0:1]
	v_mov_b64_e32 v[28:29], v[12:13]
	v_mov_b64_e32 v[26:27], v[10:11]
	v_mov_b64_e32 v[24:25], v[8:9]
	v_mov_b64_e32 v[22:23], v[6:7]
	v_mov_b64_e32 v[20:21], v[4:5]
	v_mov_b64_e32 v[18:19], v[2:3]
	v_mov_b64_e32 v[16:17], v[0:1]
	s_mov_b32 s86, 0
	s_cmp_eq_u32 s22, 0x7e0000
	s_mov_b64 s[4:5], -1
	s_cbranch_scc0 .LBB0_519

.LBB0_521:
	s_setprio 0
	s_and_saveexec_b64 s[4:5], s[0:1]
	ds_write_b32 v226, v144
	s_or_b64 exec, exec, s[4:5]
	s_waitcnt lgkmcnt(0)
	v_add_u32_e32 v136, s21, v210
	ds_read_b128 v[128:131], v136
	ds_read_b128 v[132:135], v136 offset:32
	s_ashr_i32 s21, s20, 31
	s_lshl_b64 s[0:1], s[20:21], 12
	ds_read_b128 v[138:141], v136 offset:96
	s_waitcnt lgkmcnt(2)
	v_rcp_f32_e32 v142, v128
	v_rcp_f32_e32 v145, v129
	v_rcp_f32_e32 v152, v130
	v_rcp_f32_e32 v161, v131
	ds_read_b128 v[128:131], v136 offset:64
	s_waitcnt lgkmcnt(2)
	v_rcp_f32_e32 v162, v132
	v_rcp_f32_e32 v163, v133
	v_rcp_f32_e32 v164, v134
	v_rcp_f32_e32 v165, v135
	s_waitcnt lgkmcnt(0)
	v_rcp_f32_e32 v137, v128
	v_rcp_f32_e32 v136, v129
	v_rcp_f32_e32 v135, v130
	v_rcp_f32_e32 v134, v131
	v_rcp_f32_e32 v133, v138
	v_rcp_f32_e32 v132, v139
	v_rcp_f32_e32 v131, v140
	v_rcp_f32_e32 v130, v141
	s_add_u32 s0, s62, s0
	s_addc_u32 s1, s63, s1
	s_mov_b64 s[4:5], -1
	s_andn2_b64 vcc, exec, s[18:19]
	v_lshlrev_b32_e32 v210, 2, v219
	v_lshlrev_b32_e32 v128, 14, v218
	v_mul_f32_e32 v153, v0, v142
	v_mul_f32_e32 v154, v112, v142
	v_mul_f32_e32 v155, v96, v142
	v_mul_f32_e32 v156, v80, v142
	v_mul_f32_e32 v157, v64, v142
	v_mul_f32_e32 v158, v48, v142
	v_mul_f32_e32 v159, v32, v142
	v_mul_f32_e32 v160, v16, v142
	v_mul_f32_e32 v138, v1, v145
	v_mul_f32_e32 v139, v113, v145
	v_mul_f32_e32 v140, v97, v145
	v_mul_f32_e32 v141, v81, v145
	v_mul_f32_e32 v142, v65, v145
	v_mul_f32_e32 v143, v49, v145
	v_mul_f32_e32 v144, v33, v145
	v_mul_f32_e32 v145, v17, v145
	v_mul_f32_e32 v146, v2, v152
	v_mul_f32_e32 v114, v114, v152
	v_mul_f32_e32 v147, v98, v152
	v_mul_f32_e32 v148, v82, v152
	v_mul_f32_e32 v149, v66, v152
	v_mul_f32_e32 v150, v50, v152
	v_mul_f32_e32 v151, v34, v152
	v_mul_f32_e32 v152, v18, v152
	v_mul_f32_e32 v82, v3, v161
	v_mul_f32_e32 v96, v115, v161
	v_mul_f32_e32 v97, v99, v161
	v_mul_f32_e32 v83, v83, v161
	v_mul_f32_e32 v98, v67, v161
	v_mul_f32_e32 v99, v51, v161
	v_mul_f32_e32 v112, v35, v161
	v_mul_f32_e32 v113, v19, v161
	v_mul_f32_e32 v48, v4, v162
	v_mul_f32_e32 v49, v116, v162
	v_mul_f32_e32 v50, v100, v162
	v_mul_f32_e32 v51, v84, v162
	v_mul_f32_e32 v64, v68, v162
	v_mul_f32_e32 v52, v52, v162
	v_mul_f32_e32 v36, v36, v162
	v_mul_f32_e32 v65, v20, v162
	v_mul_f32_e32 v66, v5, v163
	v_mul_f32_e32 v67, v117, v163
	v_mul_f32_e32 v68, v101, v163
	v_mul_f32_e32 v80, v85, v163
	v_mul_f32_e32 v69, v69, v163
	v_mul_f32_e32 v53, v53, v163
	v_mul_f32_e32 v37, v37, v163
	v_mul_f32_e32 v81, v21, v163
	v_mul_f32_e32 v4, v6, v164
	v_mul_f32_e32 v5, v118, v164
	v_mul_f32_e32 v6, v102, v164
	v_mul_f32_e32 v16, v86, v164
	v_mul_f32_e32 v17, v70, v164
	v_mul_f32_e32 v18, v54, v164
	v_mul_f32_e32 v19, v38, v164
	v_mul_f32_e32 v20, v22, v164
	v_mul_f32_e32 v7, v7, v165
	v_mul_f32_e32 v21, v119, v165
	v_mul_f32_e32 v22, v103, v165
	v_mul_f32_e32 v32, v87, v165
	v_mul_f32_e32 v33, v71, v165
	v_mul_f32_e32 v34, v55, v165
	v_mul_f32_e32 v35, v39, v165
	v_mul_f32_e32 v23, v23, v165
	s_cbranch_vccnz .LBB0_525
	v_lshl_add_u64 v[2:3], s[0:1], 0, v[210:211]
	v_mov_b32_e32 v129, v211
	v_lshl_add_u64 v[0:1], v[2:3], 0, v[128:129]
	global_load_dword v39, v[0:1], off
	global_load_dword v100, v[0:1], off offset:128
	global_load_dword v101, v[0:1], off offset:256
	global_load_dword v102, v[0:1], off offset:384
	global_load_dword v103, v[0:1], off offset:512
	global_load_dword v115, v[0:1], off offset:640
	global_load_dword v116, v[0:1], off offset:768
	global_load_dword v117, v[0:1], off offset:896
	v_lshlrev_b32_e32 v38, 2, v218
	v_or_b32_e32 v118, 1, v38
	v_mov_b32_e32 v1, v211
	v_lshlrev_b32_e32 v0, 12, v118
	v_lshl_add_u64 v[54:55], v[2:3], 0, v[0:1]
	global_load_dword v119, v[54:55], off
	global_load_dword v129, v[54:55], off offset:128
	global_load_dword v161, v[54:55], off offset:256
	global_load_dword v162, v[54:55], off offset:384
	global_load_dword v164, v[54:55], off offset:512
	global_load_dword v166, v[54:55], off offset:640
	global_load_dword v167, v[54:55], off offset:768
	v_or_b32_e32 v163, 2, v38
	v_or_b32_e32 v165, 3, v38
	v_mov_b32_e32 v71, v211
	v_mov_b32_e32 v85, v211
	v_lshlrev_b32_e32 v70, 12, v163
	v_lshlrev_b32_e32 v84, 12, v165
	v_lshl_add_u64 v[70:71], v[2:3], 0, v[70:71]
	v_lshl_add_u64 v[84:85], v[2:3], 0, v[84:85]
	global_load_dword v168, v[54:55], off offset:896
	global_load_dword v169, v[70:71], off
	global_load_dword v170, v[70:71], off offset:128
	global_load_dword v171, v[70:71], off offset:256
	global_load_dword v172, v[70:71], off offset:384
	global_load_dword v173, v[70:71], off offset:512
	global_load_dword v174, v[70:71], off offset:640
	global_load_dword v175, v[70:71], off offset:768
	s_nop 0
	global_load_dword v70, v[70:71], off offset:896
	s_nop 0
	global_load_dword v176, v[84:85], off
	global_load_dword v177, v[84:85], off offset:128
	global_load_dword v178, v[84:85], off offset:256
	global_load_dword v179, v[84:85], off offset:384
	global_load_dword v180, v[84:85], off offset:512
	global_load_dword v181, v[84:85], off offset:640
	global_load_dword v182, v[84:85], off offset:768
	s_nop 0
	global_load_dword v84, v[84:85], off offset:896
	s_lshl_b64 s[4:5], s[20:21], 10
	s_lshl_b64 s[4:5], s[4:5], 1
	s_add_u32 s4, s64, s4
	v_lshlrev_b32_e32 v0, 1, v219
	s_addc_u32 s5, s65, s5
	v_lshlrev_b32_e32 v86, 13, v218
	v_mov_b32_e32 v87, v211
	v_lshl_add_u64 v[0:1], s[4:5], 0, v[0:1]
	v_lshl_add_u64 v[54:55], v[0:1], 0, v[86:87]
	s_mov_b64 s[4:5], 0
	s_waitcnt vmcnt(31)
	v_fma_f32 v39, -v209, v153, v39
	s_waitcnt vmcnt(30)
	v_fma_f32 v71, -v209, v154, v100
	s_waitcnt vmcnt(29)
	v_fma_f32 v85, -v209, v155, v101
	s_waitcnt vmcnt(28)
	v_fma_f32 v86, -v209, v156, v102
	s_waitcnt vmcnt(27)
	v_fma_f32 v87, -v209, v157, v103
	s_waitcnt vmcnt(26)
	v_fma_f32 v100, -v209, v158, v115
	s_waitcnt vmcnt(25)
	v_fma_f32 v101, -v209, v159, v116
	v_bfe_u32 v102, v39, 16, 1
	v_bfe_u32 v103, v71, 16, 1
	v_bfe_u32 v115, v85, 16, 1
	v_bfe_u32 v116, v86, 16, 1
	v_bfe_u32 v183, v87, 16, 1
	v_add3_u32 v39, v39, v102, s39
	v_bfe_u32 v102, v100, 16, 1
	v_add3_u32 v71, v71, v103, s39
	v_bfe_u32 v103, v101, 16, 1
	v_add3_u32 v85, v85, v115, s39
	v_add3_u32 v86, v86, v116, s39
	v_add3_u32 v87, v87, v183, s39
	v_add3_u32 v100, v100, v102, s39
	v_add3_u32 v101, v101, v103, s39
	global_store_short_d16_hi v[54:55], v39, off
	global_store_short_d16_hi v[54:55], v71, off offset:64
	global_store_short_d16_hi v[54:55], v85, off offset:128
	global_store_short_d16_hi v[54:55], v86, off offset:192
	global_store_short_d16_hi v[54:55], v87, off offset:256
	global_store_short_d16_hi v[54:55], v100, off offset:320
	global_store_short_d16_hi v[54:55], v101, off offset:384
	s_waitcnt vmcnt(31)
	v_fma_f32 v39, -v209, v160, v117
	v_bfe_u32 v71, v39, 16, 1
	v_add3_u32 v39, v39, v71, s39
	global_store_short_d16_hi v[54:55], v39, off offset:448
	s_waitcnt vmcnt(31)
	v_fma_f32 v39, -v209, v138, v119
	v_lshlrev_b32_e32 v54, 11, v118
	v_mov_b32_e32 v55, v211
	v_bfe_u32 v71, v39, 16, 1
	v_lshl_add_u64 v[54:55], v[0:1], 0, v[54:55]
	v_add3_u32 v39, v39, v71, s39
	global_store_short_d16_hi v[54:55], v39, off
	s_waitcnt vmcnt(31)
	v_fma_f32 v39, -v209, v139, v129
	v_bfe_u32 v71, v39, 16, 1
	v_add3_u32 v39, v39, v71, s39
	global_store_short_d16_hi v[54:55], v39, off offset:64
	s_waitcnt vmcnt(31)
	v_fma_f32 v39, -v209, v140, v161
	v_bfe_u32 v71, v39, 16, 1
	v_add3_u32 v39, v39, v71, s39
	global_store_short_d16_hi v[54:55], v39, off offset:128
	s_waitcnt vmcnt(31)
	v_fma_f32 v39, -v209, v141, v162
	v_bfe_u32 v71, v39, 16, 1
	v_add3_u32 v39, v39, v71, s39
	global_store_short_d16_hi v[54:55], v39, off offset:192
	s_waitcnt vmcnt(31)
	v_fma_f32 v39, -v209, v142, v164
	v_bfe_u32 v71, v39, 16, 1
	v_add3_u32 v39, v39, v71, s39
	global_store_short_d16_hi v[54:55], v39, off offset:256
	s_waitcnt vmcnt(31)
	v_fma_f32 v39, -v209, v143, v166
	v_bfe_u32 v71, v39, 16, 1
	v_add3_u32 v39, v39, v71, s39
	global_store_short_d16_hi v[54:55], v39, off offset:320
	s_waitcnt vmcnt(31)
	v_fma_f32 v39, -v209, v144, v167
	v_bfe_u32 v71, v39, 16, 1
	v_add3_u32 v39, v39, v71, s39
	global_store_short_d16_hi v[54:55], v39, off offset:384
	s_waitcnt vmcnt(31)
	v_fma_f32 v39, -v209, v145, v168
	v_bfe_u32 v71, v39, 16, 1
	v_add3_u32 v39, v39, v71, s39
	global_store_short_d16_hi v[54:55], v39, off offset:448
	s_waitcnt vmcnt(31)
	v_fma_f32 v39, -v209, v146, v169
	v_lshlrev_b32_e32 v54, 11, v163
	v_mov_b32_e32 v55, v211
	v_bfe_u32 v71, v39, 16, 1
	v_lshl_add_u64 v[54:55], v[0:1], 0, v[54:55]
	v_add3_u32 v39, v39, v71, s39
	global_store_short_d16_hi v[54:55], v39, off
	s_waitcnt vmcnt(31)
	v_fma_f32 v39, -v209, v114, v170
	v_bfe_u32 v71, v39, 16, 1
	v_add3_u32 v39, v39, v71, s39
	global_store_short_d16_hi v[54:55], v39, off offset:64
	s_waitcnt vmcnt(31)
	v_fma_f32 v39, -v209, v147, v171
	v_bfe_u32 v71, v39, 16, 1
	v_add3_u32 v39, v39, v71, s39
	global_store_short_d16_hi v[54:55], v39, off offset:128
	s_waitcnt vmcnt(31)
	v_fma_f32 v39, -v209, v148, v172
	v_bfe_u32 v71, v39, 16, 1
	v_add3_u32 v39, v39, v71, s39
	global_store_short_d16_hi v[54:55], v39, off offset:192
	s_waitcnt vmcnt(31)
	v_fma_f32 v39, -v209, v149, v173
	v_bfe_u32 v71, v39, 16, 1
	v_add3_u32 v39, v39, v71, s39
	global_store_short_d16_hi v[54:55], v39, off offset:256
	s_waitcnt vmcnt(31)
	v_fma_f32 v39, -v209, v150, v174
	v_bfe_u32 v71, v39, 16, 1
	v_add3_u32 v39, v39, v71, s39
	global_store_short_d16_hi v[54:55], v39, off offset:320
	s_waitcnt vmcnt(31)
	v_fma_f32 v39, -v209, v151, v175
	v_bfe_u32 v71, v39, 16, 1
	v_add3_u32 v39, v39, v71, s39
	global_store_short_d16_hi v[54:55], v39, off offset:384
	s_waitcnt vmcnt(31)
	v_fma_f32 v39, -v209, v152, v70
	v_bfe_u32 v70, v39, 16, 1
	v_add3_u32 v39, v39, v70, s39
	global_store_short_d16_hi v[54:55], v39, off offset:448
	v_or_b32_e32 v39, 8, v38
	v_lshlrev_b32_e32 v70, 12, v39
	v_mov_b32_e32 v71, v211
	v_lshl_add_u64 v[70:71], v[2:3], 0, v[70:71]
	global_load_dword v85, v[70:71], off
	global_load_dword v100, v[70:71], off offset:128
	global_load_dword v115, v[70:71], off offset:640
	s_waitcnt vmcnt(34)
	v_fma_f32 v86, -v209, v82, v176
	v_lshlrev_b32_e32 v54, 11, v165
	v_mov_b32_e32 v55, v211
	v_bfe_u32 v87, v86, 16, 1
	v_lshl_add_u64 v[54:55], v[0:1], 0, v[54:55]
	v_add3_u32 v86, v86, v87, s39
	global_store_short_d16_hi v[54:55], v86, off
	s_waitcnt vmcnt(34)
	v_fma_f32 v86, -v209, v96, v177
	global_load_dword v87, v[70:71], off offset:256
	v_bfe_u32 v101, v86, 16, 1
	v_add3_u32 v86, v86, v101, s39
	global_store_short_d16_hi v[54:55], v86, off offset:64
	global_load_dword v86, v[70:71], off offset:384
	s_waitcnt vmcnt(36)
	v_fma_f32 v101, -v209, v97, v178
	v_bfe_u32 v102, v101, 16, 1
	v_add3_u32 v101, v101, v102, s39
	global_load_dword v102, v[70:71], off offset:512
	v_or_b32_e32 v118, 9, v38
	global_store_short_d16_hi v[54:55], v101, off offset:128
	s_waitcnt vmcnt(37)
	v_fma_f32 v101, -v209, v83, v179
	v_bfe_u32 v103, v101, 16, 1
	v_add3_u32 v101, v101, v103, s39
	global_store_short_d16_hi v[54:55], v101, off offset:192
	s_waitcnt vmcnt(37)
	v_fma_f32 v101, -v209, v98, v180
	global_load_dword v103, v[70:71], off offset:768
	v_bfe_u32 v116, v101, 16, 1
	v_add3_u32 v101, v101, v116, s39
	global_store_short_d16_hi v[54:55], v101, off offset:256
	global_load_dword v101, v[70:71], off offset:896
	v_lshlrev_b32_e32 v70, 12, v118
	v_mov_b32_e32 v71, v211
	v_lshl_add_u64 v[70:71], v[2:3], 0, v[70:71]
	s_waitcnt vmcnt(39)
	v_fma_f32 v116, -v209, v99, v181
	global_load_dword v119, v[70:71], off
	v_bfe_u32 v117, v116, 16, 1
	v_add3_u32 v116, v116, v117, s39
	global_store_short_d16_hi v[54:55], v116, off offset:320
	s_waitcnt vmcnt(40)
	v_fma_f32 v116, -v209, v112, v182
	global_load_dword v117, v[70:71], off offset:128
	v_bfe_u32 v129, v116, 16, 1
	v_add3_u32 v116, v116, v129, s39
	global_store_short_d16_hi v[54:55], v116, off offset:384
	global_load_dword v116, v[70:71], off offset:256
	s_waitcnt vmcnt(42)
	v_fma_f32 v84, -v209, v113, v84
	v_bfe_u32 v129, v84, 16, 1
	v_add3_u32 v84, v84, v129, s39
	global_load_dword v129, v[70:71], off offset:384
	v_or_b32_e32 v171, 11, v38
	global_store_short_d16_hi v[54:55], v84, off offset:448
	global_load_dword v84, v[70:71], off offset:512
	s_nop 0
	global_load_dword v161, v[70:71], off offset:640
	global_load_dword v162, v[70:71], off offset:768
	s_nop 0
	global_load_dword v70, v[70:71], off offset:896
	v_or_b32_e32 v71, 10, v38
	v_lshlrev_b32_e32 v54, 12, v71
	v_mov_b32_e32 v55, v211
	v_lshl_add_u64 v[54:55], v[2:3], 0, v[54:55]
	global_load_dword v163, v[54:55], off
	global_load_dword v164, v[54:55], off offset:128
	global_load_dword v165, v[54:55], off offset:256
	global_load_dword v166, v[54:55], off offset:384
	global_load_dword v167, v[54:55], off offset:512
	global_load_dword v168, v[54:55], off offset:640
	global_load_dword v169, v[54:55], off offset:768
	global_load_dword v170, v[54:55], off offset:896
	v_lshlrev_b32_e32 v54, 12, v171
	v_mov_b32_e32 v55, v211
	v_lshl_add_u64 v[54:55], v[2:3], 0, v[54:55]
	global_load_dword v172, v[54:55], off
	global_load_dword v173, v[54:55], off offset:128
	global_load_dword v174, v[54:55], off offset:256
	global_load_dword v175, v[54:55], off offset:384
	global_load_dword v176, v[54:55], off offset:512
	global_load_dword v177, v[54:55], off offset:640
	global_load_dword v178, v[54:55], off offset:768
	global_load_dword v179, v[54:55], off offset:896
	v_lshlrev_b32_e32 v54, 11, v39
	v_mov_b32_e32 v55, v211
	v_lshl_add_u64 v[54:55], v[0:1], 0, v[54:55]
	s_waitcnt vmcnt(39)
	v_fma_f32 v39, -v209, v48, v85
	v_bfe_u32 v85, v39, 16, 1
	v_add3_u32 v39, v39, v85, s39
	global_store_short_d16_hi v[54:55], v39, off
	s_waitcnt vmcnt(39)
	v_fma_f32 v39, -v209, v49, v100
	v_bfe_u32 v85, v39, 16, 1
	v_add3_u32 v39, v39, v85, s39
	global_store_short_d16_hi v[54:55], v39, off offset:64
	s_waitcnt vmcnt(37)
	v_fma_f32 v39, -v209, v50, v87
	v_bfe_u32 v85, v39, 16, 1
	v_add3_u32 v39, v39, v85, s39
	global_store_short_d16_hi v[54:55], v39, off offset:128
	s_waitcnt vmcnt(36)
	v_fma_f32 v39, -v209, v51, v86
	v_bfe_u32 v85, v39, 16, 1
	v_add3_u32 v39, v39, v85, s39
	global_store_short_d16_hi v[54:55], v39, off offset:192
	s_waitcnt vmcnt(36)
	v_fma_f32 v39, -v209, v64, v102
	v_bfe_u32 v85, v39, 16, 1
	v_add3_u32 v39, v39, v85, s39
	global_store_short_d16_hi v[54:55], v39, off offset:256
	v_fma_f32 v39, -v209, v52, v115
	v_bfe_u32 v85, v39, 16, 1
	v_add3_u32 v39, v39, v85, s39
	global_store_short_d16_hi v[54:55], v39, off offset:320
	s_waitcnt vmcnt(35)
	v_fma_f32 v39, -v209, v36, v103
	v_bfe_u32 v85, v39, 16, 1
	v_add3_u32 v39, v39, v85, s39
	global_store_short_d16_hi v[54:55], v39, off offset:384
	s_waitcnt vmcnt(34)
	v_fma_f32 v39, -v209, v65, v101
	v_bfe_u32 v85, v39, 16, 1
	v_add3_u32 v39, v39, v85, s39
	global_store_short_d16_hi v[54:55], v39, off offset:448
	v_lshlrev_b32_e32 v54, 11, v118
	s_waitcnt vmcnt(34)
	v_fma_f32 v39, -v209, v66, v119
	v_mov_b32_e32 v55, v211
	v_bfe_u32 v85, v39, 16, 1
	v_lshl_add_u64 v[54:55], v[0:1], 0, v[54:55]
	v_add3_u32 v39, v39, v85, s39
	global_store_short_d16_hi v[54:55], v39, off
	s_waitcnt vmcnt(33)
	v_fma_f32 v39, -v209, v67, v117
	v_bfe_u32 v85, v39, 16, 1
	v_add3_u32 v39, v39, v85, s39
	global_store_short_d16_hi v[54:55], v39, off offset:64
	s_waitcnt vmcnt(32)
	v_fma_f32 v39, -v209, v68, v116
	v_bfe_u32 v85, v39, 16, 1
	v_add3_u32 v39, v39, v85, s39
	global_store_short_d16_hi v[54:55], v39, off offset:128
	s_waitcnt vmcnt(32)
	v_fma_f32 v39, -v209, v80, v129
	v_bfe_u32 v85, v39, 16, 1
	v_add3_u32 v39, v39, v85, s39
	global_store_short_d16_hi v[54:55], v39, off offset:192
	s_waitcnt vmcnt(31)
	v_fma_f32 v39, -v209, v69, v84
	v_bfe_u32 v84, v39, 16, 1
	v_add3_u32 v39, v39, v84, s39
	global_store_short_d16_hi v[54:55], v39, off offset:256
	s_waitcnt vmcnt(31)
	v_fma_f32 v39, -v209, v53, v161
	v_bfe_u32 v84, v39, 16, 1
	v_add3_u32 v39, v39, v84, s39
	global_store_short_d16_hi v[54:55], v39, off offset:320
	s_waitcnt vmcnt(31)
	v_fma_f32 v39, -v209, v37, v162
	v_bfe_u32 v84, v39, 16, 1
	v_add3_u32 v39, v39, v84, s39
	global_store_short_d16_hi v[54:55], v39, off offset:384
	s_waitcnt vmcnt(31)
	v_fma_f32 v39, -v209, v81, v70
	v_bfe_u32 v70, v39, 16, 1
	v_add3_u32 v39, v39, v70, s39
	global_store_short_d16_hi v[54:55], v39, off offset:448
	s_waitcnt vmcnt(31)
	v_fma_f32 v39, -v209, v4, v163
	v_lshlrev_b32_e32 v54, 11, v71
	v_mov_b32_e32 v55, v211
	v_bfe_u32 v70, v39, 16, 1
	v_lshl_add_u64 v[54:55], v[0:1], 0, v[54:55]
	v_add3_u32 v39, v39, v70, s39
	global_store_short_d16_hi v[54:55], v39, off
	s_waitcnt vmcnt(31)
	v_fma_f32 v39, -v209, v5, v164
	v_bfe_u32 v70, v39, 16, 1
	v_add3_u32 v39, v39, v70, s39
	global_store_short_d16_hi v[54:55], v39, off offset:64
	s_waitcnt vmcnt(31)
	v_fma_f32 v39, -v209, v6, v165
	v_bfe_u32 v70, v39, 16, 1
	v_add3_u32 v39, v39, v70, s39
	global_store_short_d16_hi v[54:55], v39, off offset:128
	s_waitcnt vmcnt(31)
	v_fma_f32 v39, -v209, v16, v166
	v_bfe_u32 v70, v39, 16, 1
	v_add3_u32 v39, v39, v70, s39
	global_store_short_d16_hi v[54:55], v39, off offset:192
	s_waitcnt vmcnt(31)
	v_fma_f32 v39, -v209, v17, v167
	v_bfe_u32 v70, v39, 16, 1
	v_add3_u32 v39, v39, v70, s39
	global_store_short_d16_hi v[54:55], v39, off offset:256
	s_waitcnt vmcnt(31)
	v_fma_f32 v39, -v209, v18, v168
	v_bfe_u32 v70, v39, 16, 1
	v_add3_u32 v39, v39, v70, s39
	global_store_short_d16_hi v[54:55], v39, off offset:320
	s_waitcnt vmcnt(31)
	v_fma_f32 v39, -v209, v19, v169
	v_bfe_u32 v70, v39, 16, 1
	v_add3_u32 v39, v39, v70, s39
	global_store_short_d16_hi v[54:55], v39, off offset:384
	s_waitcnt vmcnt(31)
	v_fma_f32 v39, -v209, v20, v170
	v_bfe_u32 v70, v39, 16, 1
	v_add3_u32 v39, v39, v70, s39
	global_store_short_d16_hi v[54:55], v39, off offset:448
	v_or_b32_e32 v39, 16, v38
	v_lshlrev_b32_e32 v70, 12, v39
	v_mov_b32_e32 v71, v211
	v_lshl_add_u64 v[70:71], v[2:3], 0, v[70:71]
	global_load_dword v84, v[70:71], off
	s_waitcnt vmcnt(32)
	v_fma_f32 v85, -v209, v7, v172
	v_lshlrev_b32_e32 v54, 11, v171
	v_mov_b32_e32 v55, v211
	v_bfe_u32 v86, v85, 16, 1
	v_lshl_add_u64 v[54:55], v[0:1], 0, v[54:55]
	v_add3_u32 v85, v85, v86, s39
	global_store_short_d16_hi v[54:55], v85, off
	global_load_dword v85, v[70:71], off offset:128
	s_waitcnt vmcnt(33)
	v_fma_f32 v86, -v209, v21, v173
	v_bfe_u32 v87, v86, 16, 1
	v_add3_u32 v86, v86, v87, s39
	global_store_short_d16_hi v[54:55], v86, off offset:64
	global_load_dword v86, v[70:71], off offset:256
	s_waitcnt vmcnt(34)
	v_fma_f32 v87, -v209, v22, v174
	v_bfe_u32 v100, v87, 16, 1
	v_add3_u32 v87, v87, v100, s39
	global_store_short_d16_hi v[54:55], v87, off offset:128
	global_load_dword v87, v[70:71], off offset:384
	s_waitcnt vmcnt(35)
	v_fma_f32 v100, -v209, v32, v175
	v_bfe_u32 v101, v100, 16, 1
	v_add3_u32 v100, v100, v101, s39
	global_store_short_d16_hi v[54:55], v100, off offset:192
	global_load_dword v100, v[70:71], off offset:512
	s_waitcnt vmcnt(36)
	v_fma_f32 v101, -v209, v33, v176
	v_bfe_u32 v102, v101, 16, 1
	v_add3_u32 v101, v101, v102, s39
	global_store_short_d16_hi v[54:55], v101, off offset:256
	global_load_dword v101, v[70:71], off offset:640
	s_waitcnt vmcnt(37)
	v_fma_f32 v102, -v209, v34, v177
	v_bfe_u32 v103, v102, 16, 1
	v_add3_u32 v102, v102, v103, s39
	global_store_short_d16_hi v[54:55], v102, off offset:320
	global_load_dword v102, v[70:71], off offset:768
	s_waitcnt vmcnt(38)
	v_fma_f32 v103, -v209, v35, v178
	v_bfe_u32 v115, v103, 16, 1
	v_add3_u32 v103, v103, v115, s39
	global_store_short_d16_hi v[54:55], v103, off offset:384
	global_load_dword v103, v[70:71], off offset:896
	s_waitcnt vmcnt(39)
	v_fma_f32 v70, -v209, v23, v179
	v_bfe_u32 v71, v70, 16, 1
	v_or_b32_e32 v116, 17, v38
	v_add3_u32 v115, v70, v71, s39
	v_lshlrev_b32_e32 v70, 12, v116
	v_mov_b32_e32 v71, v211
	v_lshl_add_u64 v[70:71], v[2:3], 0, v[70:71]
	global_load_dword v117, v[70:71], off
	v_or_b32_e32 v171, 19, v38
	global_store_short_d16_hi v[54:55], v115, off offset:448
	global_load_dword v115, v[70:71], off offset:128
	s_nop 0
	global_load_dword v118, v[70:71], off offset:256
	global_load_dword v119, v[70:71], off offset:384
	global_load_dword v129, v[70:71], off offset:512
	global_load_dword v161, v[70:71], off offset:640
	global_load_dword v162, v[70:71], off offset:768
	s_nop 0
	global_load_dword v70, v[70:71], off offset:896
	v_or_b32_e32 v71, 18, v38
	v_lshlrev_b32_e32 v54, 12, v71
	v_mov_b32_e32 v55, v211
	v_lshl_add_u64 v[54:55], v[2:3], 0, v[54:55]
	global_load_dword v163, v[54:55], off
	global_load_dword v164, v[54:55], off offset:128
	global_load_dword v165, v[54:55], off offset:256
	global_load_dword v166, v[54:55], off offset:384
	global_load_dword v167, v[54:55], off offset:512
	global_load_dword v168, v[54:55], off offset:640
	global_load_dword v169, v[54:55], off offset:768
	global_load_dword v170, v[54:55], off offset:896
	v_lshlrev_b32_e32 v54, 12, v171
	v_mov_b32_e32 v55, v211
	v_lshl_add_u64 v[54:55], v[2:3], 0, v[54:55]
	global_load_dword v172, v[54:55], off
	global_load_dword v173, v[54:55], off offset:128
	global_load_dword v174, v[54:55], off offset:256
	global_load_dword v175, v[54:55], off offset:384
	global_load_dword v176, v[54:55], off offset:512
	global_load_dword v177, v[54:55], off offset:640
	global_load_dword v178, v[54:55], off offset:768
	global_load_dword v179, v[54:55], off offset:896
	v_lshlrev_b32_e32 v54, 11, v39
	v_mul_f32_e32 v39, v8, v137
	v_mov_b32_e32 v55, v211
	v_lshl_add_u64 v[54:55], v[0:1], 0, v[54:55]
	s_waitcnt vmcnt(39)
	v_fma_f32 v39, -v209, v39, v84
	v_bfe_u32 v84, v39, 16, 1
	v_add3_u32 v39, v39, v84, s39
	global_store_short_d16_hi v[54:55], v39, off
	v_mul_f32_e32 v39, v120, v137
	s_waitcnt vmcnt(38)
	v_fma_f32 v39, -v209, v39, v85
	v_bfe_u32 v84, v39, 16, 1
	v_add3_u32 v39, v39, v84, s39
	global_store_short_d16_hi v[54:55], v39, off offset:64
	v_mul_f32_e32 v39, v104, v137
	s_waitcnt vmcnt(37)
	v_fma_f32 v39, -v209, v39, v86
	v_bfe_u32 v84, v39, 16, 1
	v_add3_u32 v39, v39, v84, s39
	global_store_short_d16_hi v[54:55], v39, off offset:128
	v_mul_f32_e32 v39, v88, v137
	s_waitcnt vmcnt(36)
	v_fma_f32 v39, -v209, v39, v87
	v_bfe_u32 v84, v39, 16, 1
	v_add3_u32 v39, v39, v84, s39
	global_store_short_d16_hi v[54:55], v39, off offset:192
	v_mul_f32_e32 v39, v72, v137
	s_waitcnt vmcnt(35)
	v_fma_f32 v39, -v209, v39, v100
	v_bfe_u32 v84, v39, 16, 1
	v_add3_u32 v39, v39, v84, s39
	global_store_short_d16_hi v[54:55], v39, off offset:256
	v_mul_f32_e32 v39, v56, v137
	s_waitcnt vmcnt(34)
	v_fma_f32 v39, -v209, v39, v101
	v_bfe_u32 v84, v39, 16, 1
	v_add3_u32 v39, v39, v84, s39
	global_store_short_d16_hi v[54:55], v39, off offset:320
	v_mul_f32_e32 v39, v40, v137
	s_waitcnt vmcnt(33)
	v_fma_f32 v39, -v209, v39, v102
	v_bfe_u32 v84, v39, 16, 1
	v_add3_u32 v39, v39, v84, s39
	global_store_short_d16_hi v[54:55], v39, off offset:384
	v_mul_f32_e32 v39, v24, v137
	s_waitcnt vmcnt(32)
	v_fma_f32 v39, -v209, v39, v103
	v_bfe_u32 v84, v39, 16, 1
	v_add3_u32 v39, v39, v84, s39
	global_store_short_d16_hi v[54:55], v39, off offset:448
	v_mul_f32_e32 v39, v9, v136
	v_lshlrev_b32_e32 v54, 11, v116
	v_mov_b32_e32 v55, v211
	v_lshl_add_u64 v[54:55], v[0:1], 0, v[54:55]
	s_waitcnt vmcnt(32)
	v_fma_f32 v39, -v209, v39, v117
	v_bfe_u32 v84, v39, 16, 1
	v_add3_u32 v39, v39, v84, s39
	global_store_short_d16_hi v[54:55], v39, off
	v_mul_f32_e32 v39, v121, v136
	s_waitcnt vmcnt(31)
	v_fma_f32 v39, -v209, v39, v115
	v_bfe_u32 v84, v39, 16, 1
	v_add3_u32 v39, v39, v84, s39
	global_store_short_d16_hi v[54:55], v39, off offset:64
	v_mul_f32_e32 v39, v105, v136
	s_waitcnt vmcnt(31)
	v_fma_f32 v39, -v209, v39, v118
	v_bfe_u32 v84, v39, 16, 1
	v_add3_u32 v39, v39, v84, s39
	global_store_short_d16_hi v[54:55], v39, off offset:128
	v_mul_f32_e32 v39, v89, v136
	s_waitcnt vmcnt(31)
	v_fma_f32 v39, -v209, v39, v119
	v_bfe_u32 v84, v39, 16, 1
	v_add3_u32 v39, v39, v84, s39
	global_store_short_d16_hi v[54:55], v39, off offset:192
	v_mul_f32_e32 v39, v73, v136
	s_waitcnt vmcnt(31)
	v_fma_f32 v39, -v209, v39, v129
	v_bfe_u32 v84, v39, 16, 1
	v_add3_u32 v39, v39, v84, s39
	global_store_short_d16_hi v[54:55], v39, off offset:256
	v_mul_f32_e32 v39, v57, v136
	s_waitcnt vmcnt(31)
	v_fma_f32 v39, -v209, v39, v161
	v_bfe_u32 v84, v39, 16, 1
	v_add3_u32 v39, v39, v84, s39
	global_store_short_d16_hi v[54:55], v39, off offset:320
	v_mul_f32_e32 v39, v41, v136
	s_waitcnt vmcnt(31)
	v_fma_f32 v39, -v209, v39, v162
	v_bfe_u32 v84, v39, 16, 1
	v_add3_u32 v39, v39, v84, s39
	global_store_short_d16_hi v[54:55], v39, off offset:384
	v_mul_f32_e32 v39, v25, v136
	s_waitcnt vmcnt(31)
	v_fma_f32 v39, -v209, v39, v70
	v_bfe_u32 v70, v39, 16, 1
	v_add3_u32 v39, v39, v70, s39
	global_store_short_d16_hi v[54:55], v39, off offset:448
	v_mul_f32_e32 v39, v10, v135
	s_waitcnt vmcnt(31)
	v_fma_f32 v39, -v209, v39, v163
	v_lshlrev_b32_e32 v54, 11, v71
	v_mov_b32_e32 v55, v211
	v_bfe_u32 v70, v39, 16, 1
	v_lshl_add_u64 v[54:55], v[0:1], 0, v[54:55]
	v_add3_u32 v39, v39, v70, s39
	global_store_short_d16_hi v[54:55], v39, off
	v_mul_f32_e32 v39, v122, v135
	s_waitcnt vmcnt(31)
	v_fma_f32 v39, -v209, v39, v164
	v_bfe_u32 v70, v39, 16, 1
	v_add3_u32 v39, v39, v70, s39
	global_store_short_d16_hi v[54:55], v39, off offset:64
	v_mul_f32_e32 v39, v106, v135
	s_waitcnt vmcnt(31)
	v_fma_f32 v39, -v209, v39, v165
	v_bfe_u32 v70, v39, 16, 1
	v_add3_u32 v39, v39, v70, s39
	global_store_short_d16_hi v[54:55], v39, off offset:128
	v_mul_f32_e32 v39, v90, v135
	s_waitcnt vmcnt(31)
	v_fma_f32 v39, -v209, v39, v166
	v_bfe_u32 v70, v39, 16, 1
	v_add3_u32 v39, v39, v70, s39
	global_store_short_d16_hi v[54:55], v39, off offset:192
	v_mul_f32_e32 v39, v74, v135
	s_waitcnt vmcnt(31)
	v_fma_f32 v39, -v209, v39, v167
	v_bfe_u32 v70, v39, 16, 1
	v_add3_u32 v39, v39, v70, s39
	global_store_short_d16_hi v[54:55], v39, off offset:256
	v_mul_f32_e32 v39, v58, v135
	s_waitcnt vmcnt(31)
	v_fma_f32 v39, -v209, v39, v168
	v_bfe_u32 v70, v39, 16, 1
	v_add3_u32 v39, v39, v70, s39
	global_store_short_d16_hi v[54:55], v39, off offset:320
	v_mul_f32_e32 v39, v42, v135
	s_waitcnt vmcnt(31)
	v_fma_f32 v39, -v209, v39, v169
	v_bfe_u32 v70, v39, 16, 1
	v_add3_u32 v39, v39, v70, s39
	global_store_short_d16_hi v[54:55], v39, off offset:384
	v_mul_f32_e32 v39, v26, v135
	s_waitcnt vmcnt(31)
	v_fma_f32 v39, -v209, v39, v170
	v_bfe_u32 v70, v39, 16, 1
	v_add3_u32 v39, v39, v70, s39
	global_store_short_d16_hi v[54:55], v39, off offset:448
	v_mul_f32_e32 v39, v11, v134
	s_waitcnt vmcnt(31)
	v_fma_f32 v39, -v209, v39, v172
	v_bfe_u32 v70, v39, 16, 1
	v_or_b32_e32 v85, 24, v38
	v_add3_u32 v39, v39, v70, s39
	v_lshlrev_b32_e32 v70, 12, v85
	v_mov_b32_e32 v71, v211
	v_lshlrev_b32_e32 v54, 11, v171
	v_mov_b32_e32 v55, v211
	v_lshl_add_u64 v[70:71], v[2:3], 0, v[70:71]
	v_lshl_add_u64 v[54:55], v[0:1], 0, v[54:55]
	global_load_dword v86, v[70:71], off
	global_load_dword v103, v[70:71], off offset:640
	v_or_b32_e32 v116, 25, v38
	global_store_short_d16_hi v[54:55], v39, off
	v_mul_f32_e32 v39, v123, v134
	s_waitcnt vmcnt(33)
	v_fma_f32 v39, -v209, v39, v173
	v_bfe_u32 v84, v39, 16, 1
	v_add3_u32 v39, v39, v84, s39
	global_load_dword v84, v[70:71], off offset:128
	s_nop 0
	global_store_short_d16_hi v[54:55], v39, off offset:64
	v_mul_f32_e32 v39, v107, v134
	s_waitcnt vmcnt(34)
	v_fma_f32 v39, -v209, v39, v174
	v_bfe_u32 v87, v39, 16, 1
	v_add3_u32 v39, v39, v87, s39
	global_load_dword v87, v[70:71], off offset:256
	s_nop 0
	global_store_short_d16_hi v[54:55], v39, off offset:128
	v_mul_f32_e32 v39, v91, v134
	s_waitcnt vmcnt(35)
	v_fma_f32 v39, -v209, v39, v175
	v_bfe_u32 v100, v39, 16, 1
	v_add3_u32 v39, v39, v100, s39
	global_load_dword v100, v[70:71], off offset:384
	s_nop 0
	global_store_short_d16_hi v[54:55], v39, off offset:192
	v_mul_f32_e32 v39, v75, v134
	s_waitcnt vmcnt(36)
	v_fma_f32 v39, -v209, v39, v176
	v_bfe_u32 v101, v39, 16, 1
	v_add3_u32 v39, v39, v101, s39
	global_load_dword v101, v[70:71], off offset:512
	s_nop 0
	global_store_short_d16_hi v[54:55], v39, off offset:256
	v_mul_f32_e32 v39, v59, v134
	s_waitcnt vmcnt(37)
	v_fma_f32 v39, -v209, v39, v177
	v_bfe_u32 v102, v39, 16, 1
	v_add3_u32 v39, v39, v102, s39
	global_store_short_d16_hi v[54:55], v39, off offset:320
	v_mul_f32_e32 v39, v43, v134
	s_waitcnt vmcnt(37)
	v_fma_f32 v39, -v209, v39, v178
	global_load_dword v102, v[70:71], off offset:768
	v_bfe_u32 v115, v39, 16, 1
	v_add3_u32 v39, v39, v115, s39
	global_store_short_d16_hi v[54:55], v39, off offset:384
	v_mul_f32_e32 v39, v27, v134
	global_load_dword v115, v[70:71], off offset:896
	s_waitcnt vmcnt(39)
	v_fma_f32 v39, -v209, v39, v179
	v_bfe_u32 v70, v39, 16, 1
	v_add3_u32 v39, v39, v70, s39
	v_lshlrev_b32_e32 v70, 12, v116
	v_mov_b32_e32 v71, v211
	v_lshl_add_u64 v[70:71], v[2:3], 0, v[70:71]
	global_load_dword v117, v[70:71], off
	s_nop 0
	global_store_short_d16_hi v[54:55], v39, off offset:448
	global_load_dword v118, v[70:71], off offset:128
	global_load_dword v119, v[70:71], off offset:256
	global_load_dword v129, v[70:71], off offset:384
	global_load_dword v161, v[70:71], off offset:512
	global_load_dword v162, v[70:71], off offset:640
	global_load_dword v163, v[70:71], off offset:768
	s_nop 0
	global_load_dword v70, v[70:71], off offset:896
	v_or_b32_e32 v71, 26, v38
	v_lshlrev_b32_e32 v54, 12, v71
	v_mov_b32_e32 v55, v211
	v_lshl_add_u64 v[54:55], v[2:3], 0, v[54:55]
	global_load_dword v164, v[54:55], off
	global_load_dword v165, v[54:55], off offset:128
	global_load_dword v166, v[54:55], off offset:256
	global_load_dword v167, v[54:55], off offset:384
	global_load_dword v168, v[54:55], off offset:512
	global_load_dword v169, v[54:55], off offset:640
	global_load_dword v170, v[54:55], off offset:768
	s_nop 0
	global_load_dword v54, v[54:55], off offset:896
	v_or_b32_e32 v55, 27, v38
	v_lshlrev_b32_e32 v38, 12, v55
	v_mov_b32_e32 v39, v211
	v_lshl_add_u64 v[2:3], v[2:3], 0, v[38:39]
	global_load_dword v38, v[2:3], off
	global_load_dword v39, v[2:3], off offset:128
	global_load_dword v171, v[2:3], off offset:256
	global_load_dword v172, v[2:3], off offset:384
	global_load_dword v173, v[2:3], off offset:512
	global_load_dword v174, v[2:3], off offset:640
	global_load_dword v175, v[2:3], off offset:768
	global_load_dword v176, v[2:3], off offset:896
	v_lshlrev_b32_e32 v2, 11, v85
	v_mul_f32_e32 v85, v12, v133
	v_mov_b32_e32 v3, v211
	v_lshl_add_u64 v[2:3], v[0:1], 0, v[2:3]
	s_waitcnt vmcnt(39)
	v_fma_f32 v85, -v209, v85, v86
	v_bfe_u32 v86, v85, 16, 1
	v_add3_u32 v85, v85, v86, s39
	global_store_short_d16_hi v[2:3], v85, off
	v_mul_f32_e32 v85, v124, v133
	s_waitcnt vmcnt(37)
	v_fma_f32 v84, -v209, v85, v84
	v_bfe_u32 v85, v84, 16, 1
	v_add3_u32 v84, v84, v85, s39
	global_store_short_d16_hi v[2:3], v84, off offset:64
	v_mul_f32_e32 v84, v108, v133
	s_waitcnt vmcnt(36)
	v_fma_f32 v84, -v209, v84, v87
	v_bfe_u32 v85, v84, 16, 1
	v_add3_u32 v84, v84, v85, s39
	global_store_short_d16_hi v[2:3], v84, off offset:128
	v_mul_f32_e32 v84, v92, v133
	s_waitcnt vmcnt(35)
	v_fma_f32 v84, -v209, v84, v100
	v_bfe_u32 v85, v84, 16, 1
	v_add3_u32 v84, v84, v85, s39
	global_store_short_d16_hi v[2:3], v84, off offset:192
	v_mul_f32_e32 v84, v76, v133
	s_waitcnt vmcnt(34)
	v_fma_f32 v84, -v209, v84, v101
	v_bfe_u32 v85, v84, 16, 1
	v_add3_u32 v84, v84, v85, s39
	global_store_short_d16_hi v[2:3], v84, off offset:256
	v_mul_f32_e32 v84, v60, v133
	v_fma_f32 v84, -v209, v84, v103
	v_bfe_u32 v85, v84, 16, 1
	v_add3_u32 v84, v84, v85, s39
	global_store_short_d16_hi v[2:3], v84, off offset:320
	v_mul_f32_e32 v84, v44, v133
	s_waitcnt vmcnt(33)
	v_fma_f32 v84, -v209, v84, v102
	v_bfe_u32 v85, v84, 16, 1
	v_add3_u32 v84, v84, v85, s39
	global_store_short_d16_hi v[2:3], v84, off offset:384
	v_mul_f32_e32 v84, v28, v133
	s_waitcnt vmcnt(32)
	v_fma_f32 v84, -v209, v84, v115
	v_bfe_u32 v85, v84, 16, 1
	v_add3_u32 v84, v84, v85, s39
	global_store_short_d16_hi v[2:3], v84, off offset:448
	v_mul_f32_e32 v84, v13, v132
	v_lshlrev_b32_e32 v2, 11, v116
	v_mov_b32_e32 v3, v211
	s_waitcnt vmcnt(32)
	v_fma_f32 v84, -v209, v84, v117
	v_bfe_u32 v85, v84, 16, 1
	v_lshl_add_u64 v[2:3], v[0:1], 0, v[2:3]
	v_add3_u32 v84, v84, v85, s39
	global_store_short_d16_hi v[2:3], v84, off
	v_mul_f32_e32 v84, v125, v132
	s_waitcnt vmcnt(31)
	v_fma_f32 v84, -v209, v84, v118
	v_bfe_u32 v85, v84, 16, 1
	v_add3_u32 v84, v84, v85, s39
	global_store_short_d16_hi v[2:3], v84, off offset:64
	v_mul_f32_e32 v84, v109, v132
	s_waitcnt vmcnt(31)
	v_fma_f32 v84, -v209, v84, v119
	v_bfe_u32 v85, v84, 16, 1
	v_add3_u32 v84, v84, v85, s39
	global_store_short_d16_hi v[2:3], v84, off offset:128
	v_mul_f32_e32 v84, v93, v132
	s_waitcnt vmcnt(31)
	v_fma_f32 v84, -v209, v84, v129
	v_bfe_u32 v85, v84, 16, 1
	v_add3_u32 v84, v84, v85, s39
	global_store_short_d16_hi v[2:3], v84, off offset:192
	v_mul_f32_e32 v84, v77, v132
	s_waitcnt vmcnt(31)
	v_fma_f32 v84, -v209, v84, v161
	v_bfe_u32 v85, v84, 16, 1
	v_add3_u32 v84, v84, v85, s39
	global_store_short_d16_hi v[2:3], v84, off offset:256
	v_mul_f32_e32 v84, v61, v132
	s_waitcnt vmcnt(31)
	v_fma_f32 v84, -v209, v84, v162
	v_bfe_u32 v85, v84, 16, 1
	v_add3_u32 v84, v84, v85, s39
	global_store_short_d16_hi v[2:3], v84, off offset:320
	v_mul_f32_e32 v84, v45, v132
	s_waitcnt vmcnt(31)
	v_fma_f32 v84, -v209, v84, v163
	v_bfe_u32 v85, v84, 16, 1
	v_add3_u32 v84, v84, v85, s39
	global_store_short_d16_hi v[2:3], v84, off offset:384
	v_mul_f32_e32 v84, v29, v132
	s_waitcnt vmcnt(31)
	v_fma_f32 v70, -v209, v84, v70
	v_bfe_u32 v84, v70, 16, 1
	v_add3_u32 v70, v70, v84, s39
	global_store_short_d16_hi v[2:3], v70, off offset:448
	v_mul_f32_e32 v70, v14, v131
	s_waitcnt vmcnt(31)
	v_fma_f32 v70, -v209, v70, v164
	v_lshlrev_b32_e32 v2, 11, v71
	v_mov_b32_e32 v3, v211
	v_bfe_u32 v71, v70, 16, 1
	v_lshl_add_u64 v[2:3], v[0:1], 0, v[2:3]
	v_add3_u32 v70, v70, v71, s39
	global_store_short_d16_hi v[2:3], v70, off
	v_mul_f32_e32 v70, v126, v131
	s_waitcnt vmcnt(31)
	v_fma_f32 v70, -v209, v70, v165
	v_bfe_u32 v71, v70, 16, 1
	v_add3_u32 v70, v70, v71, s39
	global_store_short_d16_hi v[2:3], v70, off offset:64
	v_mul_f32_e32 v70, v110, v131
	s_waitcnt vmcnt(31)
	v_fma_f32 v70, -v209, v70, v166
	v_bfe_u32 v71, v70, 16, 1
	v_add3_u32 v70, v70, v71, s39
	global_store_short_d16_hi v[2:3], v70, off offset:128
	v_mul_f32_e32 v70, v94, v131
	s_waitcnt vmcnt(31)
	v_fma_f32 v70, -v209, v70, v167
	v_bfe_u32 v71, v70, 16, 1
	v_add3_u32 v70, v70, v71, s39
	global_store_short_d16_hi v[2:3], v70, off offset:192
	v_mul_f32_e32 v70, v78, v131
	s_waitcnt vmcnt(31)
	v_fma_f32 v70, -v209, v70, v168
	v_bfe_u32 v71, v70, 16, 1
	v_add3_u32 v70, v70, v71, s39
	global_store_short_d16_hi v[2:3], v70, off offset:256
	v_mul_f32_e32 v70, v62, v131
	s_waitcnt vmcnt(31)
	v_fma_f32 v70, -v209, v70, v169
	v_bfe_u32 v71, v70, 16, 1
	v_add3_u32 v70, v70, v71, s39
	global_store_short_d16_hi v[2:3], v70, off offset:320
	v_mul_f32_e32 v70, v46, v131
	s_waitcnt vmcnt(31)
	v_fma_f32 v70, -v209, v70, v170
	v_bfe_u32 v71, v70, 16, 1
	v_add3_u32 v70, v70, v71, s39
	global_store_short_d16_hi v[2:3], v70, off offset:384
	v_mul_f32_e32 v70, v30, v131
	s_waitcnt vmcnt(31)
	v_fma_f32 v54, -v209, v70, v54
	v_bfe_u32 v70, v54, 16, 1
	v_add3_u32 v54, v54, v70, s39
	global_store_short_d16_hi v[2:3], v54, off offset:448
	v_lshlrev_b32_e32 v2, 11, v55
	v_mov_b32_e32 v3, v211
	v_lshl_add_u64 v[0:1], v[0:1], 0, v[2:3]
	v_mul_f32_e32 v2, v15, v130
	s_waitcnt vmcnt(31)
	v_fma_f32 v2, -v209, v2, v38
	v_bfe_u32 v3, v2, 16, 1
	v_add3_u32 v2, v2, v3, s39
	global_store_short_d16_hi v[0:1], v2, off
	v_mul_f32_e32 v2, v127, v130
	s_waitcnt vmcnt(31)
	v_fma_f32 v2, -v209, v2, v39
	v_bfe_u32 v3, v2, 16, 1
	v_add3_u32 v2, v2, v3, s39
	global_store_short_d16_hi v[0:1], v2, off offset:64
	v_mul_f32_e32 v2, v111, v130
	s_waitcnt vmcnt(31)
	v_fma_f32 v2, -v209, v2, v171
	v_bfe_u32 v3, v2, 16, 1
	v_add3_u32 v2, v2, v3, s39
	global_store_short_d16_hi v[0:1], v2, off offset:128
	v_mul_f32_e32 v2, v95, v130
	s_waitcnt vmcnt(31)
	v_fma_f32 v2, -v209, v2, v172
	v_bfe_u32 v3, v2, 16, 1
	v_add3_u32 v2, v2, v3, s39
	global_store_short_d16_hi v[0:1], v2, off offset:192
	v_mul_f32_e32 v2, v79, v130
	s_waitcnt vmcnt(31)
	v_fma_f32 v2, -v209, v2, v173
	v_bfe_u32 v3, v2, 16, 1
	v_add3_u32 v2, v2, v3, s39
	global_store_short_d16_hi v[0:1], v2, off offset:256
	v_mul_f32_e32 v2, v63, v130
	s_waitcnt vmcnt(31)
	v_fma_f32 v2, -v209, v2, v174
	v_bfe_u32 v3, v2, 16, 1
	v_add3_u32 v2, v2, v3, s39
	global_store_short_d16_hi v[0:1], v2, off offset:320
	v_mul_f32_e32 v2, v47, v130
	s_waitcnt vmcnt(31)
	v_fma_f32 v2, -v209, v2, v175
	v_bfe_u32 v3, v2, 16, 1
	v_add3_u32 v2, v2, v3, s39
	global_store_short_d16_hi v[0:1], v2, off offset:384
	v_mul_f32_e32 v2, v31, v130
	s_waitcnt vmcnt(31)
	v_fma_f32 v2, -v209, v2, v176
	v_bfe_u32 v3, v2, 16, 1
	v_add3_u32 v2, v2, v3, s39
	global_store_short_d16_hi v[0:1], v2, off offset:448

.LBB0_902:
	s_xor_b64 s[18:19], s[4:5], -1
	s_lshl_b64 s[4:5], s[0:1], 1
	s_add_u32 s22, s62, s4
	s_addc_u32 s23, s63, s5
	v_mov_b32_e32 v2, v208
	s_add_u32 s0, s64, s4
	s_addc_u32 s1, s65, s5
	v_readfirstlane_b32 s20, v2
	s_ashr_i32 s24, s20, 6
	s_cmp_lt_u32 s24, 4
	s_cbranch_scc1 .Lprio0_skip
	s_setprio 1
.Lprio0_skip:
	s_and_b32 s20, s20, 0x3fffffc0
	s_lshl_b32 s20, s20, 2
	v_and_b32_e32 v219, 31, v2
	s_add_i32 s21, s20, 0
	s_lshl_b32 s20, s24, 5
	v_or_b32_e32 v0, s20, v219
	s_waitcnt lgkmcnt(0)
	v_ashrrev_i32_e32 v1, 31, v0
	v_bfe_u32 v218, v2, 5, 1
	v_lshlrev_b64 v[0:1], 11, v[0:1]
	v_lshl_add_u64 v[0:1], s[22:23], 0, v[0:1]
	v_lshlrev_b32_e32 v210, 4, v218
	v_lshl_add_u64 v[0:1], v[0:1], 0, v[210:211]
	global_load_dwordx4 v[160:163], v[0:1], off
	global_load_dwordx4 v[164:167], v[0:1], off offset:32
	global_load_dwordx4 v[168:171], v[0:1], off offset:64
	global_load_dwordx4 v[172:175], v[0:1], off offset:96
	global_load_dwordx4 v[176:179], v[0:1], off offset:128
	global_load_dwordx4 v[180:183], v[0:1], off offset:160
	global_load_dwordx4 v[184:187], v[0:1], off offset:192
	global_load_dwordx4 v[188:191], v[0:1], off offset:224
	s_lshl_b32 s22, s24, 3
	v_bfe_u32 v1, v2, 4, 2
	v_or_b32_e32 v0, s22, v1
	v_bitop3_b32 v4, v1, v2, 15 bitop3:0x78
	v_ashrrev_i32_e32 v1, 31, v0
	v_lshlrev_b64 v[212:213], 10, v[0:1]
	v_or_b32_e32 v0, 4, v0
	v_and_b32_e32 v3, 15, v2
	v_ashrrev_i32_e32 v1, 31, v0
	v_bitop3_b32 v3, v0, v3, 7 bitop3:0x6c
	v_lshlrev_b64 v[214:215], 10, v[0:1]
	v_bfe_u32 v0, v2, 2, 3
	v_bitop3_b32 v0, s22, -13, v0 bitop3:0xc8
	v_lshrrev_b32_e32 v1, 1, v2
	s_lshl_b32 s22, s24, 2
	v_and_b32_e32 v1, 8, v1
	s_and_b32 s22, s22, 4
	v_or3_b32 v0, v0, v1, s22
	s_add_i32 s21, s21, 0x24000
	v_ashrrev_i32_e32 v1, 31, v0
	v_lshlrev_b32_e32 v11, 3, v2
	s_lshl_b32 s22, s24, 11
	v_lshl_or_b32 v212, v4, 3, v212
	v_lshlrev_b64 v[216:217], 10, v[0:1]
	v_and_b32_e32 v0, 32, v2
	v_and_b32_e32 v1, 24, v11
	s_cmp_lg_u32 0, -1
	v_or3_b32 v216, v216, v1, v0
	v_lshlrev_b64 v[0:1], 1, v[212:213]
	s_cselect_b32 s23, 0, 0
	v_and_b32_e32 v10, 63, v2
	v_lshl_or_b32 v214, v3, 3, v214
	v_lshlrev_b32_e32 v12, 4, v2
	v_lshlrev_b32_e32 v13, 1, v2
	v_lshl_add_u64 v[2:3], s[0:1], 0, v[0:1]
	s_add_i32 s79, s22, s23
	s_mov_b32 s25, m0
	s_mov_b32 m0, s79
	s_nop 0
	global_load_lds_dwordx4 v[2:3], off
	s_mov_b32 m0, s25
	v_lshlrev_b64 v[2:3], 1, v[214:215]
	s_or_b32 s25, s22, 0x400
	v_lshl_add_u64 v[4:5], s[0:1], 0, v[2:3]
	s_add_i32 s81, s25, s23
	s_mov_b32 s84, m0
	s_mov_b32 m0, s81
	s_nop 0
	global_load_lds_dwordx4 v[4:5], off
	s_mov_b32 m0, s84
	s_lshl_b32 s24, s24, 12
	v_lshlrev_b64 v[4:5], 1, v[216:217]
	s_add_i32 s84, s23, 0xc000
	v_lshl_add_u64 v[6:7], s[14:15], 0, v[4:5]
	s_add_i32 s81, s24, s84
	s_mov_b32 s85, m0
	s_mov_b32 m0, s81
	s_nop 0
	global_load_lds_dwordx4 v[6:7], off
	s_mov_b32 m0, s85
	s_or_b32 s85, s24, 0x400
	s_add_i32 s86, s85, s84
	v_lshl_add_u64 v[8:9], v[6:7], 0, s[8:9]
	s_mov_b32 s87, m0
	s_mov_b32 m0, s86
	s_nop 0
	global_load_lds_dwordx4 v[8:9], off
	s_mov_b32 m0, s87
	s_or_b32 s86, s24, 0x800
	s_add_i32 s87, s86, s84
	v_lshl_add_u64 v[8:9], v[6:7], 0, s[10:11]
	s_mov_b32 s96, m0
	s_mov_b32 m0, s87
	s_nop 0
	global_load_lds_dwordx4 v[8:9], off
	s_mov_b32 m0, s96
	s_or_b32 s87, s24, 0xc00
	s_add_i32 s96, s87, s84
	s_add_u32 s0, s0, 0x20000
	v_lshl_add_u64 v[6:7], v[6:7], 0, s[12:13]
	s_mov_b32 s97, m0
	s_mov_b32 m0, s96
	s_nop 0
	global_load_lds_dwordx4 v[6:7], off
	s_mov_b32 m0, s97
	s_addc_u32 s1, s1, 0
	s_add_i32 s96, s23, 0x4000
	v_lshl_add_u64 v[0:1], s[0:1], 0, v[0:1]
	s_add_i32 s22, s22, s96
	s_mov_b32 s97, m0
	s_mov_b32 m0, s22
	s_nop 0
	global_load_lds_dwordx4 v[0:1], off
	s_mov_b32 m0, s97
	v_lshl_add_u64 v[0:1], s[0:1], 0, v[2:3]
	s_add_i32 s25, s25, s96
	s_mov_b32 s0, m0
	s_mov_b32 m0, s25
	s_nop 0
	global_load_lds_dwordx4 v[0:1], off
	s_mov_b32 m0, s0
	s_add_i32 s23, s23, 0x14000
	v_lshl_add_u64 v[0:1], s[16:17], 0, v[4:5]
	s_add_i32 s24, s24, s23
	s_mov_b32 s0, m0
	s_mov_b32 m0, s24
	s_nop 0
	global_load_lds_dwordx4 v[0:1], off
	s_mov_b32 m0, s0
	v_lshl_add_u64 v[2:3], v[0:1], 0, s[8:9]
	s_add_i32 s85, s85, s23
	s_mov_b32 s0, m0
	s_mov_b32 m0, s85
	s_nop 0
	global_load_lds_dwordx4 v[2:3], off
	s_mov_b32 m0, s0
	v_lshl_add_u64 v[2:3], v[0:1], 0, s[10:11]
	s_add_i32 s86, s86, s23
	s_mov_b32 s0, m0
	s_mov_b32 m0, s86
	s_nop 0
	global_load_lds_dwordx4 v[2:3], off
	s_mov_b32 m0, s0
	v_lshl_add_u64 v[0:1], v[0:1], 0, s[12:13]
	s_add_i32 s87, s87, s23
	s_mov_b32 s0, m0
	s_mov_b32 m0, s87
	s_nop 0
	global_load_lds_dwordx4 v[0:1], off
	s_mov_b32 m0, s0
	v_and_b32_e32 v0, 0x118, v11
	v_and_b32_e32 v14, 0xc0, v12
	s_movk_i32 s0, 0x70
	v_and_or_b32 v0, v13, 32, v0
	v_and_b32_e32 v1, 0x70, v12
	v_bitop3_b32 v221, v210, v12, s0 bitop3:0x78
	s_movk_i32 s0, 0xc0
	v_add3_u32 v230, v14, s84, v0
	v_mov_b32_e32 v14, v211
	v_mov_b32_e32 v15, v211
	v_bitop3_b32 v222, v210, v1, 32 bitop3:0x36
	v_bitop3_b32 v223, v210, v1, 64 bitop3:0x36
	v_bitop3_b32 v225, v210, v1, s38 bitop3:0x36
	v_bitop3_b32 v226, v210, v1, s39 bitop3:0x36
	v_bitop3_b32 v227, v210, v1, s40 bitop3:0x36
	v_bitop3_b32 v228, v210, v1, s0 bitop3:0x36
	v_bitop3_b32 v229, v210, v1, s41 bitop3:0x36
	v_cmp_gt_u32_e64 s[0:1], 32, v10
	s_add_u32 s84, s74, s4
	v_mov_b32_e32 v0, v211
	v_mov_b32_e32 v1, v211
	v_mov_b32_e32 v2, v211
	v_mov_b32_e32 v3, v211
	v_mov_b32_e32 v4, v211
	v_mov_b32_e32 v5, v211
	v_mov_b32_e32 v6, v211
	v_mov_b32_e32 v7, v211
	v_mov_b32_e32 v8, v211
	v_mov_b32_e32 v9, v211
	v_mov_b32_e32 v10, v211
	v_mov_b32_e32 v11, v211
	v_mov_b32_e32 v12, v211
	v_mov_b32_e32 v13, v211
	v_mov_b64_e32 v[126:127], v[14:15]
	v_mov_b64_e32 v[110:111], v[14:15]
	v_mov_b64_e32 v[94:95], v[14:15]
	v_mov_b64_e32 v[78:79], v[14:15]
	v_mov_b64_e32 v[62:63], v[14:15]
	v_mov_b64_e32 v[46:47], v[14:15]
	v_mov_b64_e32 v[30:31], v[14:15]
	s_mov_b32 s78, 2
	s_mov_b32 s80, 0
	v_lshlrev_b32_e32 v220, 8, v219
	v_lshl_add_u32 v224, v219, 2, s21
	s_addc_u32 s85, s75, s5
	v_mov_b32_e32 v232, 0
	v_mov_b32_e32 v231, 0xf149f2ca
	s_mov_b64 s[22:23], 0
	v_mov_b64_e32 v[124:125], v[12:13]
	v_mov_b64_e32 v[122:123], v[10:11]
	v_mov_b64_e32 v[120:121], v[8:9]
	v_mov_b64_e32 v[118:119], v[6:7]
	v_mov_b64_e32 v[116:117], v[4:5]
	v_mov_b64_e32 v[114:115], v[2:3]
	v_mov_b64_e32 v[112:113], v[0:1]
	v_mov_b64_e32 v[108:109], v[12:13]
	v_mov_b64_e32 v[106:107], v[10:11]
	v_mov_b64_e32 v[104:105], v[8:9]
	v_mov_b64_e32 v[102:103], v[6:7]
	v_mov_b64_e32 v[100:101], v[4:5]
	v_mov_b64_e32 v[98:99], v[2:3]
	v_mov_b64_e32 v[96:97], v[0:1]
	v_mov_b64_e32 v[92:93], v[12:13]
	v_mov_b64_e32 v[90:91], v[10:11]
	v_mov_b64_e32 v[88:89], v[8:9]
	v_mov_b64_e32 v[86:87], v[6:7]
	v_mov_b64_e32 v[84:85], v[4:5]
	v_mov_b64_e32 v[82:83], v[2:3]
	v_mov_b64_e32 v[80:81], v[0:1]
	v_mov_b64_e32 v[76:77], v[12:13]
	v_mov_b64_e32 v[74:75], v[10:11]
	v_mov_b64_e32 v[72:73], v[8:9]
	v_mov_b64_e32 v[70:71], v[6:7]
	v_mov_b64_e32 v[68:69], v[4:5]
	v_mov_b64_e32 v[66:67], v[2:3]
	v_mov_b64_e32 v[64:65], v[0:1]
	v_mov_b64_e32 v[60:61], v[12:13]
	v_mov_b64_e32 v[58:59], v[10:11]
	v_mov_b64_e32 v[56:57], v[8:9]
	v_mov_b64_e32 v[54:55], v[6:7]
	v_mov_b64_e32 v[52:53], v[4:5]
	v_mov_b64_e32 v[50:51], v[2:3]
	v_mov_b64_e32 v[48:49], v[0:1]
	v_mov_b64_e32 v[44:45], v[12:13]
	v_mov_b64_e32 v[42:43], v[10:11]
	v_mov_b64_e32 v[40:41], v[8:9]
	v_mov_b64_e32 v[38:39], v[6:7]
	v_mov_b64_e32 v[36:37], v[4:5]
	v_mov_b64_e32 v[34:35], v[2:3]
	v_mov_b64_e32 v[32:33], v[0:1]
	v_mov_b64_e32 v[28:29], v[12:13]
	v_mov_b64_e32 v[26:27], v[10:11]
	v_mov_b64_e32 v[24:25], v[8:9]
	v_mov_b64_e32 v[22:23], v[6:7]
	v_mov_b64_e32 v[20:21], v[4:5]
	v_mov_b64_e32 v[18:19], v[2:3]
	v_mov_b64_e32 v[16:17], v[0:1]
	s_mov_b32 s86, 0
	s_cmp_eq_u32 s22, 0x7e0000
	s_mov_b64 s[4:5], -1
	s_cbranch_scc0 .LBB0_912

.LBB0_914:
	s_setprio 0
	s_and_saveexec_b64 s[4:5], s[0:1]
	ds_write_b32 v224, v144
	s_or_b64 exec, exec, s[4:5]
	s_waitcnt lgkmcnt(0)
	v_add_u32_e32 v136, s21, v210
	ds_read_b128 v[128:131], v136
	ds_read_b128 v[132:135], v136 offset:32
	s_ashr_i32 s21, s20, 31
	s_lshl_b64 s[0:1], s[20:21], 12
	ds_read_b128 v[138:141], v136 offset:96
	s_waitcnt lgkmcnt(2)
	v_rcp_f32_e32 v142, v128
	v_rcp_f32_e32 v145, v129
	v_rcp_f32_e32 v152, v130
	v_rcp_f32_e32 v161, v131
	ds_read_b128 v[128:131], v136 offset:64
	s_waitcnt lgkmcnt(2)
	v_rcp_f32_e32 v162, v132
	v_rcp_f32_e32 v163, v133
	v_rcp_f32_e32 v164, v134
	v_rcp_f32_e32 v165, v135
	s_waitcnt lgkmcnt(0)
	v_rcp_f32_e32 v137, v128
	v_rcp_f32_e32 v136, v129
	v_rcp_f32_e32 v135, v130
	v_rcp_f32_e32 v134, v131
	v_rcp_f32_e32 v133, v138
	v_rcp_f32_e32 v132, v139
	v_rcp_f32_e32 v131, v140
	v_rcp_f32_e32 v130, v141
	s_add_u32 s0, s66, s0
	s_addc_u32 s1, s67, s1
	s_mov_b64 s[4:5], -1
	s_andn2_b64 vcc, exec, s[18:19]
	v_lshlrev_b32_e32 v210, 2, v219
	v_lshlrev_b32_e32 v128, 14, v218
	v_mul_f32_e32 v153, v0, v142
	v_mul_f32_e32 v154, v112, v142
	v_mul_f32_e32 v155, v96, v142
	v_mul_f32_e32 v156, v80, v142
	v_mul_f32_e32 v157, v64, v142
	v_mul_f32_e32 v158, v48, v142
	v_mul_f32_e32 v159, v32, v142
	v_mul_f32_e32 v160, v16, v142
	v_mul_f32_e32 v138, v1, v145
	v_mul_f32_e32 v139, v113, v145
	v_mul_f32_e32 v140, v97, v145
	v_mul_f32_e32 v141, v81, v145
	v_mul_f32_e32 v142, v65, v145
	v_mul_f32_e32 v143, v49, v145
	v_mul_f32_e32 v144, v33, v145
	v_mul_f32_e32 v145, v17, v145
	v_mul_f32_e32 v146, v2, v152
	v_mul_f32_e32 v114, v114, v152
	v_mul_f32_e32 v147, v98, v152
	v_mul_f32_e32 v148, v82, v152
	v_mul_f32_e32 v149, v66, v152
	v_mul_f32_e32 v150, v50, v152
	v_mul_f32_e32 v151, v34, v152
	v_mul_f32_e32 v152, v18, v152
	v_mul_f32_e32 v82, v3, v161
	v_mul_f32_e32 v96, v115, v161
	v_mul_f32_e32 v97, v99, v161
	v_mul_f32_e32 v83, v83, v161
	v_mul_f32_e32 v98, v67, v161
	v_mul_f32_e32 v99, v51, v161
	v_mul_f32_e32 v112, v35, v161
	v_mul_f32_e32 v113, v19, v161
	v_mul_f32_e32 v48, v4, v162
	v_mul_f32_e32 v49, v116, v162
	v_mul_f32_e32 v50, v100, v162
	v_mul_f32_e32 v51, v84, v162
	v_mul_f32_e32 v64, v68, v162
	v_mul_f32_e32 v52, v52, v162
	v_mul_f32_e32 v36, v36, v162
	v_mul_f32_e32 v65, v20, v162
	v_mul_f32_e32 v66, v5, v163
	v_mul_f32_e32 v67, v117, v163
	v_mul_f32_e32 v68, v101, v163
	v_mul_f32_e32 v80, v85, v163
	v_mul_f32_e32 v69, v69, v163
	v_mul_f32_e32 v53, v53, v163
	v_mul_f32_e32 v37, v37, v163
	v_mul_f32_e32 v81, v21, v163
	v_mul_f32_e32 v4, v6, v164
	v_mul_f32_e32 v5, v118, v164
	v_mul_f32_e32 v6, v102, v164
	v_mul_f32_e32 v16, v86, v164
	v_mul_f32_e32 v17, v70, v164
	v_mul_f32_e32 v18, v54, v164
	v_mul_f32_e32 v19, v38, v164
	v_mul_f32_e32 v20, v22, v164
	v_mul_f32_e32 v7, v7, v165
	v_mul_f32_e32 v21, v119, v165
	v_mul_f32_e32 v22, v103, v165
	v_mul_f32_e32 v32, v87, v165
	v_mul_f32_e32 v33, v71, v165
	v_mul_f32_e32 v34, v55, v165
	v_mul_f32_e32 v35, v39, v165
	v_mul_f32_e32 v23, v23, v165
	s_cbranch_vccnz .LBB0_918
	v_lshl_add_u64 v[2:3], s[0:1], 0, v[210:211]
	v_mov_b32_e32 v129, v211
	v_lshl_add_u64 v[0:1], v[2:3], 0, v[128:129]
	global_load_dword v39, v[0:1], off
	global_load_dword v100, v[0:1], off offset:128
	global_load_dword v101, v[0:1], off offset:256
	global_load_dword v102, v[0:1], off offset:384
	global_load_dword v103, v[0:1], off offset:512
	global_load_dword v115, v[0:1], off offset:640
	global_load_dword v116, v[0:1], off offset:768
	global_load_dword v117, v[0:1], off offset:896
	v_lshlrev_b32_e32 v38, 2, v218
	v_or_b32_e32 v118, 1, v38
	v_mov_b32_e32 v1, v211
	v_lshlrev_b32_e32 v0, 12, v118
	v_lshl_add_u64 v[54:55], v[2:3], 0, v[0:1]
	global_load_dword v119, v[54:55], off
	global_load_dword v129, v[54:55], off offset:128
	global_load_dword v161, v[54:55], off offset:256
	global_load_dword v162, v[54:55], off offset:384
	global_load_dword v164, v[54:55], off offset:512
	global_load_dword v166, v[54:55], off offset:640
	global_load_dword v167, v[54:55], off offset:768
	v_or_b32_e32 v163, 2, v38
	v_or_b32_e32 v165, 3, v38
	v_mov_b32_e32 v71, v211
	v_mov_b32_e32 v85, v211
	v_lshlrev_b32_e32 v70, 12, v163
	v_lshlrev_b32_e32 v84, 12, v165
	v_lshl_add_u64 v[70:71], v[2:3], 0, v[70:71]
	v_lshl_add_u64 v[84:85], v[2:3], 0, v[84:85]
	global_load_dword v168, v[54:55], off offset:896
	global_load_dword v169, v[70:71], off
	global_load_dword v170, v[70:71], off offset:128
	global_load_dword v171, v[70:71], off offset:256
	global_load_dword v172, v[70:71], off offset:384
	global_load_dword v173, v[70:71], off offset:512
	global_load_dword v174, v[70:71], off offset:640
	global_load_dword v175, v[70:71], off offset:768
	s_nop 0
	global_load_dword v70, v[70:71], off offset:896
	s_nop 0
	global_load_dword v176, v[84:85], off
	global_load_dword v177, v[84:85], off offset:128
	global_load_dword v178, v[84:85], off offset:256
	global_load_dword v179, v[84:85], off offset:384
	global_load_dword v180, v[84:85], off offset:512
	global_load_dword v181, v[84:85], off offset:640
	global_load_dword v182, v[84:85], off offset:768
	s_nop 0
	global_load_dword v84, v[84:85], off offset:896
	s_lshl_b64 s[4:5], s[20:21], 10
	s_lshl_b64 s[4:5], s[4:5], 1
	s_add_u32 s4, s68, s4
	v_lshlrev_b32_e32 v0, 1, v219
	s_addc_u32 s5, s69, s5
	v_lshlrev_b32_e32 v86, 13, v218
	v_mov_b32_e32 v87, v211
	v_lshl_add_u64 v[0:1], s[4:5], 0, v[0:1]
	v_lshl_add_u64 v[54:55], v[0:1], 0, v[86:87]
	s_mov_b64 s[4:5], 0
	s_waitcnt vmcnt(31)
	v_fma_f32 v39, -v209, v153, v39
	s_waitcnt vmcnt(30)
	v_fma_f32 v71, -v209, v154, v100
	s_waitcnt vmcnt(29)
	v_fma_f32 v85, -v209, v155, v101
	s_waitcnt vmcnt(28)
	v_fma_f32 v86, -v209, v156, v102
	s_waitcnt vmcnt(27)
	v_fma_f32 v87, -v209, v157, v103
	s_waitcnt vmcnt(26)
	v_fma_f32 v100, -v209, v158, v115
	s_waitcnt vmcnt(25)
	v_fma_f32 v101, -v209, v159, v116
	v_bfe_u32 v102, v39, 16, 1
	v_bfe_u32 v103, v71, 16, 1
	v_bfe_u32 v115, v85, 16, 1
	v_bfe_u32 v116, v86, 16, 1
	v_bfe_u32 v183, v87, 16, 1
	v_add3_u32 v39, v39, v102, s43
	v_bfe_u32 v102, v100, 16, 1
	v_add3_u32 v71, v71, v103, s43
	v_bfe_u32 v103, v101, 16, 1
	v_add3_u32 v85, v85, v115, s43
	v_add3_u32 v86, v86, v116, s43
	v_add3_u32 v87, v87, v183, s43
	v_add3_u32 v100, v100, v102, s43
	v_add3_u32 v101, v101, v103, s43
	global_store_short_d16_hi v[54:55], v39, off
	global_store_short_d16_hi v[54:55], v71, off offset:64
	global_store_short_d16_hi v[54:55], v85, off offset:128
	global_store_short_d16_hi v[54:55], v86, off offset:192
	global_store_short_d16_hi v[54:55], v87, off offset:256
	global_store_short_d16_hi v[54:55], v100, off offset:320
	global_store_short_d16_hi v[54:55], v101, off offset:384
	s_waitcnt vmcnt(31)
	v_fma_f32 v39, -v209, v160, v117
	v_bfe_u32 v71, v39, 16, 1
	v_add3_u32 v39, v39, v71, s43
	global_store_short_d16_hi v[54:55], v39, off offset:448
	s_waitcnt vmcnt(31)
	v_fma_f32 v39, -v209, v138, v119
	v_lshlrev_b32_e32 v54, 11, v118
	v_mov_b32_e32 v55, v211
	v_bfe_u32 v71, v39, 16, 1
	v_lshl_add_u64 v[54:55], v[0:1], 0, v[54:55]
	v_add3_u32 v39, v39, v71, s43
	global_store_short_d16_hi v[54:55], v39, off
	s_waitcnt vmcnt(31)
	v_fma_f32 v39, -v209, v139, v129
	v_bfe_u32 v71, v39, 16, 1
	v_add3_u32 v39, v39, v71, s43
	global_store_short_d16_hi v[54:55], v39, off offset:64
	s_waitcnt vmcnt(31)
	v_fma_f32 v39, -v209, v140, v161
	v_bfe_u32 v71, v39, 16, 1
	v_add3_u32 v39, v39, v71, s43
	global_store_short_d16_hi v[54:55], v39, off offset:128
	s_waitcnt vmcnt(31)
	v_fma_f32 v39, -v209, v141, v162
	v_bfe_u32 v71, v39, 16, 1
	v_add3_u32 v39, v39, v71, s43
	global_store_short_d16_hi v[54:55], v39, off offset:192
	s_waitcnt vmcnt(31)
	v_fma_f32 v39, -v209, v142, v164
	v_bfe_u32 v71, v39, 16, 1
	v_add3_u32 v39, v39, v71, s43
	global_store_short_d16_hi v[54:55], v39, off offset:256
	s_waitcnt vmcnt(31)
	v_fma_f32 v39, -v209, v143, v166
	v_bfe_u32 v71, v39, 16, 1
	v_add3_u32 v39, v39, v71, s43
	global_store_short_d16_hi v[54:55], v39, off offset:320
	s_waitcnt vmcnt(31)
	v_fma_f32 v39, -v209, v144, v167
	v_bfe_u32 v71, v39, 16, 1
	v_add3_u32 v39, v39, v71, s43
	global_store_short_d16_hi v[54:55], v39, off offset:384
	s_waitcnt vmcnt(31)
	v_fma_f32 v39, -v209, v145, v168
	v_bfe_u32 v71, v39, 16, 1
	v_add3_u32 v39, v39, v71, s43
	global_store_short_d16_hi v[54:55], v39, off offset:448
	s_waitcnt vmcnt(31)
	v_fma_f32 v39, -v209, v146, v169
	v_lshlrev_b32_e32 v54, 11, v163
	v_mov_b32_e32 v55, v211
	v_bfe_u32 v71, v39, 16, 1
	v_lshl_add_u64 v[54:55], v[0:1], 0, v[54:55]
	v_add3_u32 v39, v39, v71, s43
	global_store_short_d16_hi v[54:55], v39, off
	s_waitcnt vmcnt(31)
	v_fma_f32 v39, -v209, v114, v170
	v_bfe_u32 v71, v39, 16, 1
	v_add3_u32 v39, v39, v71, s43
	global_store_short_d16_hi v[54:55], v39, off offset:64
	s_waitcnt vmcnt(31)
	v_fma_f32 v39, -v209, v147, v171
	v_bfe_u32 v71, v39, 16, 1
	v_add3_u32 v39, v39, v71, s43
	global_store_short_d16_hi v[54:55], v39, off offset:128
	s_waitcnt vmcnt(31)
	v_fma_f32 v39, -v209, v148, v172
	v_bfe_u32 v71, v39, 16, 1
	v_add3_u32 v39, v39, v71, s43
	global_store_short_d16_hi v[54:55], v39, off offset:192
	s_waitcnt vmcnt(31)
	v_fma_f32 v39, -v209, v149, v173
	v_bfe_u32 v71, v39, 16, 1
	v_add3_u32 v39, v39, v71, s43
	global_store_short_d16_hi v[54:55], v39, off offset:256
	s_waitcnt vmcnt(31)
	v_fma_f32 v39, -v209, v150, v174
	v_bfe_u32 v71, v39, 16, 1
	v_add3_u32 v39, v39, v71, s43
	global_store_short_d16_hi v[54:55], v39, off offset:320
	s_waitcnt vmcnt(31)
	v_fma_f32 v39, -v209, v151, v175
	v_bfe_u32 v71, v39, 16, 1
	v_add3_u32 v39, v39, v71, s43
	global_store_short_d16_hi v[54:55], v39, off offset:384
	s_waitcnt vmcnt(31)
	v_fma_f32 v39, -v209, v152, v70
	v_bfe_u32 v70, v39, 16, 1
	v_add3_u32 v39, v39, v70, s43
	global_store_short_d16_hi v[54:55], v39, off offset:448
	v_or_b32_e32 v39, 8, v38
	v_lshlrev_b32_e32 v70, 12, v39
	v_mov_b32_e32 v71, v211
	v_lshl_add_u64 v[70:71], v[2:3], 0, v[70:71]
	global_load_dword v85, v[70:71], off
	global_load_dword v100, v[70:71], off offset:128
	global_load_dword v115, v[70:71], off offset:640
	s_waitcnt vmcnt(34)
	v_fma_f32 v86, -v209, v82, v176
	v_lshlrev_b32_e32 v54, 11, v165
	v_mov_b32_e32 v55, v211
	v_bfe_u32 v87, v86, 16, 1
	v_lshl_add_u64 v[54:55], v[0:1], 0, v[54:55]
	v_add3_u32 v86, v86, v87, s43
	global_store_short_d16_hi v[54:55], v86, off
	s_waitcnt vmcnt(34)
	v_fma_f32 v86, -v209, v96, v177
	global_load_dword v87, v[70:71], off offset:256
	v_bfe_u32 v101, v86, 16, 1
	v_add3_u32 v86, v86, v101, s43
	global_store_short_d16_hi v[54:55], v86, off offset:64
	global_load_dword v86, v[70:71], off offset:384
	s_waitcnt vmcnt(36)
	v_fma_f32 v101, -v209, v97, v178
	v_bfe_u32 v102, v101, 16, 1
	v_add3_u32 v101, v101, v102, s43
	global_load_dword v102, v[70:71], off offset:512
	v_or_b32_e32 v118, 9, v38
	global_store_short_d16_hi v[54:55], v101, off offset:128
	s_waitcnt vmcnt(37)
	v_fma_f32 v101, -v209, v83, v179
	v_bfe_u32 v103, v101, 16, 1
	v_add3_u32 v101, v101, v103, s43
	global_store_short_d16_hi v[54:55], v101, off offset:192
	s_waitcnt vmcnt(37)
	v_fma_f32 v101, -v209, v98, v180
	global_load_dword v103, v[70:71], off offset:768
	v_bfe_u32 v116, v101, 16, 1
	v_add3_u32 v101, v101, v116, s43
	global_store_short_d16_hi v[54:55], v101, off offset:256
	global_load_dword v101, v[70:71], off offset:896
	v_lshlrev_b32_e32 v70, 12, v118
	v_mov_b32_e32 v71, v211
	v_lshl_add_u64 v[70:71], v[2:3], 0, v[70:71]
	s_waitcnt vmcnt(39)
	v_fma_f32 v116, -v209, v99, v181
	global_load_dword v119, v[70:71], off
	v_bfe_u32 v117, v116, 16, 1
	v_add3_u32 v116, v116, v117, s43
	global_store_short_d16_hi v[54:55], v116, off offset:320
	s_waitcnt vmcnt(40)
	v_fma_f32 v116, -v209, v112, v182
	global_load_dword v117, v[70:71], off offset:128
	v_bfe_u32 v129, v116, 16, 1
	v_add3_u32 v116, v116, v129, s43
	global_store_short_d16_hi v[54:55], v116, off offset:384
	global_load_dword v116, v[70:71], off offset:256
	s_waitcnt vmcnt(42)
	v_fma_f32 v84, -v209, v113, v84
	v_bfe_u32 v129, v84, 16, 1
	v_add3_u32 v84, v84, v129, s43
	global_load_dword v129, v[70:71], off offset:384
	v_or_b32_e32 v171, 11, v38
	global_store_short_d16_hi v[54:55], v84, off offset:448
	global_load_dword v84, v[70:71], off offset:512
	s_nop 0
	global_load_dword v161, v[70:71], off offset:640
	global_load_dword v162, v[70:71], off offset:768
	s_nop 0
	global_load_dword v70, v[70:71], off offset:896
	v_or_b32_e32 v71, 10, v38
	v_lshlrev_b32_e32 v54, 12, v71
	v_mov_b32_e32 v55, v211
	v_lshl_add_u64 v[54:55], v[2:3], 0, v[54:55]
	global_load_dword v163, v[54:55], off
	global_load_dword v164, v[54:55], off offset:128
	global_load_dword v165, v[54:55], off offset:256
	global_load_dword v166, v[54:55], off offset:384
	global_load_dword v167, v[54:55], off offset:512
	global_load_dword v168, v[54:55], off offset:640
	global_load_dword v169, v[54:55], off offset:768
	global_load_dword v170, v[54:55], off offset:896
	v_lshlrev_b32_e32 v54, 12, v171
	v_mov_b32_e32 v55, v211
	v_lshl_add_u64 v[54:55], v[2:3], 0, v[54:55]
	global_load_dword v172, v[54:55], off
	global_load_dword v173, v[54:55], off offset:128
	global_load_dword v174, v[54:55], off offset:256
	global_load_dword v175, v[54:55], off offset:384
	global_load_dword v176, v[54:55], off offset:512
	global_load_dword v177, v[54:55], off offset:640
	global_load_dword v178, v[54:55], off offset:768
	global_load_dword v179, v[54:55], off offset:896
	v_lshlrev_b32_e32 v54, 11, v39
	v_mov_b32_e32 v55, v211
	v_lshl_add_u64 v[54:55], v[0:1], 0, v[54:55]
	s_waitcnt vmcnt(39)
	v_fma_f32 v39, -v209, v48, v85
	v_bfe_u32 v85, v39, 16, 1
	v_add3_u32 v39, v39, v85, s43
	global_store_short_d16_hi v[54:55], v39, off
	s_waitcnt vmcnt(39)
	v_fma_f32 v39, -v209, v49, v100
	v_bfe_u32 v85, v39, 16, 1
	v_add3_u32 v39, v39, v85, s43
	global_store_short_d16_hi v[54:55], v39, off offset:64
	s_waitcnt vmcnt(37)
	v_fma_f32 v39, -v209, v50, v87
	v_bfe_u32 v85, v39, 16, 1
	v_add3_u32 v39, v39, v85, s43
	global_store_short_d16_hi v[54:55], v39, off offset:128
	s_waitcnt vmcnt(36)
	v_fma_f32 v39, -v209, v51, v86
	v_bfe_u32 v85, v39, 16, 1
	v_add3_u32 v39, v39, v85, s43
	global_store_short_d16_hi v[54:55], v39, off offset:192
	s_waitcnt vmcnt(36)
	v_fma_f32 v39, -v209, v64, v102
	v_bfe_u32 v85, v39, 16, 1
	v_add3_u32 v39, v39, v85, s43
	global_store_short_d16_hi v[54:55], v39, off offset:256
	v_fma_f32 v39, -v209, v52, v115
	v_bfe_u32 v85, v39, 16, 1
	v_add3_u32 v39, v39, v85, s43
	global_store_short_d16_hi v[54:55], v39, off offset:320
	s_waitcnt vmcnt(35)
	v_fma_f32 v39, -v209, v36, v103
	v_bfe_u32 v85, v39, 16, 1
	v_add3_u32 v39, v39, v85, s43
	global_store_short_d16_hi v[54:55], v39, off offset:384
	s_waitcnt vmcnt(34)
	v_fma_f32 v39, -v209, v65, v101
	v_bfe_u32 v85, v39, 16, 1
	v_add3_u32 v39, v39, v85, s43
	global_store_short_d16_hi v[54:55], v39, off offset:448
	v_lshlrev_b32_e32 v54, 11, v118
	s_waitcnt vmcnt(34)
	v_fma_f32 v39, -v209, v66, v119
	v_mov_b32_e32 v55, v211
	v_bfe_u32 v85, v39, 16, 1
	v_lshl_add_u64 v[54:55], v[0:1], 0, v[54:55]
	v_add3_u32 v39, v39, v85, s43
	global_store_short_d16_hi v[54:55], v39, off
	s_waitcnt vmcnt(33)
	v_fma_f32 v39, -v209, v67, v117
	v_bfe_u32 v85, v39, 16, 1
	v_add3_u32 v39, v39, v85, s43
	global_store_short_d16_hi v[54:55], v39, off offset:64
	s_waitcnt vmcnt(32)
	v_fma_f32 v39, -v209, v68, v116
	v_bfe_u32 v85, v39, 16, 1
	v_add3_u32 v39, v39, v85, s43
	global_store_short_d16_hi v[54:55], v39, off offset:128
	s_waitcnt vmcnt(32)
	v_fma_f32 v39, -v209, v80, v129
	v_bfe_u32 v85, v39, 16, 1
	v_add3_u32 v39, v39, v85, s43
	global_store_short_d16_hi v[54:55], v39, off offset:192
	s_waitcnt vmcnt(31)
	v_fma_f32 v39, -v209, v69, v84
	v_bfe_u32 v84, v39, 16, 1
	v_add3_u32 v39, v39, v84, s43
	global_store_short_d16_hi v[54:55], v39, off offset:256
	s_waitcnt vmcnt(31)
	v_fma_f32 v39, -v209, v53, v161
	v_bfe_u32 v84, v39, 16, 1
	v_add3_u32 v39, v39, v84, s43
	global_store_short_d16_hi v[54:55], v39, off offset:320
	s_waitcnt vmcnt(31)
	v_fma_f32 v39, -v209, v37, v162
	v_bfe_u32 v84, v39, 16, 1
	v_add3_u32 v39, v39, v84, s43
	global_store_short_d16_hi v[54:55], v39, off offset:384
	s_waitcnt vmcnt(31)
	v_fma_f32 v39, -v209, v81, v70
	v_bfe_u32 v70, v39, 16, 1
	v_add3_u32 v39, v39, v70, s43
	global_store_short_d16_hi v[54:55], v39, off offset:448
	s_waitcnt vmcnt(31)
	v_fma_f32 v39, -v209, v4, v163
	v_lshlrev_b32_e32 v54, 11, v71
	v_mov_b32_e32 v55, v211
	v_bfe_u32 v70, v39, 16, 1
	v_lshl_add_u64 v[54:55], v[0:1], 0, v[54:55]
	v_add3_u32 v39, v39, v70, s43
	global_store_short_d16_hi v[54:55], v39, off
	s_waitcnt vmcnt(31)
	v_fma_f32 v39, -v209, v5, v164
	v_bfe_u32 v70, v39, 16, 1
	v_add3_u32 v39, v39, v70, s43
	global_store_short_d16_hi v[54:55], v39, off offset:64
	s_waitcnt vmcnt(31)
	v_fma_f32 v39, -v209, v6, v165
	v_bfe_u32 v70, v39, 16, 1
	v_add3_u32 v39, v39, v70, s43
	global_store_short_d16_hi v[54:55], v39, off offset:128
	s_waitcnt vmcnt(31)
	v_fma_f32 v39, -v209, v16, v166
	v_bfe_u32 v70, v39, 16, 1
	v_add3_u32 v39, v39, v70, s43
	global_store_short_d16_hi v[54:55], v39, off offset:192
	s_waitcnt vmcnt(31)
	v_fma_f32 v39, -v209, v17, v167
	v_bfe_u32 v70, v39, 16, 1
	v_add3_u32 v39, v39, v70, s43
	global_store_short_d16_hi v[54:55], v39, off offset:256
	s_waitcnt vmcnt(31)
	v_fma_f32 v39, -v209, v18, v168
	v_bfe_u32 v70, v39, 16, 1
	v_add3_u32 v39, v39, v70, s43
	global_store_short_d16_hi v[54:55], v39, off offset:320
	s_waitcnt vmcnt(31)
	v_fma_f32 v39, -v209, v19, v169
	v_bfe_u32 v70, v39, 16, 1
	v_add3_u32 v39, v39, v70, s43
	global_store_short_d16_hi v[54:55], v39, off offset:384
	s_waitcnt vmcnt(31)
	v_fma_f32 v39, -v209, v20, v170
	v_bfe_u32 v70, v39, 16, 1
	v_add3_u32 v39, v39, v70, s43
	global_store_short_d16_hi v[54:55], v39, off offset:448
	v_or_b32_e32 v39, 16, v38
	v_lshlrev_b32_e32 v70, 12, v39
	v_mov_b32_e32 v71, v211
	v_lshl_add_u64 v[70:71], v[2:3], 0, v[70:71]
	global_load_dword v84, v[70:71], off
	s_waitcnt vmcnt(32)
	v_fma_f32 v85, -v209, v7, v172
	v_lshlrev_b32_e32 v54, 11, v171
	v_mov_b32_e32 v55, v211
	v_bfe_u32 v86, v85, 16, 1
	v_lshl_add_u64 v[54:55], v[0:1], 0, v[54:55]
	v_add3_u32 v85, v85, v86, s43
	global_store_short_d16_hi v[54:55], v85, off
	global_load_dword v85, v[70:71], off offset:128
	s_waitcnt vmcnt(33)
	v_fma_f32 v86, -v209, v21, v173
	v_bfe_u32 v87, v86, 16, 1
	v_add3_u32 v86, v86, v87, s43
	global_store_short_d16_hi v[54:55], v86, off offset:64
	global_load_dword v86, v[70:71], off offset:256
	s_waitcnt vmcnt(34)
	v_fma_f32 v87, -v209, v22, v174
	v_bfe_u32 v100, v87, 16, 1
	v_add3_u32 v87, v87, v100, s43
	global_store_short_d16_hi v[54:55], v87, off offset:128
	global_load_dword v87, v[70:71], off offset:384
	s_waitcnt vmcnt(35)
	v_fma_f32 v100, -v209, v32, v175
	v_bfe_u32 v101, v100, 16, 1
	v_add3_u32 v100, v100, v101, s43
	global_store_short_d16_hi v[54:55], v100, off offset:192
	global_load_dword v100, v[70:71], off offset:512
	s_waitcnt vmcnt(36)
	v_fma_f32 v101, -v209, v33, v176
	v_bfe_u32 v102, v101, 16, 1
	v_add3_u32 v101, v101, v102, s43
	global_store_short_d16_hi v[54:55], v101, off offset:256
	global_load_dword v101, v[70:71], off offset:640
	s_waitcnt vmcnt(37)
	v_fma_f32 v102, -v209, v34, v177
	v_bfe_u32 v103, v102, 16, 1
	v_add3_u32 v102, v102, v103, s43
	global_store_short_d16_hi v[54:55], v102, off offset:320
	global_load_dword v102, v[70:71], off offset:768
	s_waitcnt vmcnt(38)
	v_fma_f32 v103, -v209, v35, v178
	v_bfe_u32 v115, v103, 16, 1
	v_add3_u32 v103, v103, v115, s43
	global_store_short_d16_hi v[54:55], v103, off offset:384
	global_load_dword v103, v[70:71], off offset:896
	s_waitcnt vmcnt(39)
	v_fma_f32 v70, -v209, v23, v179
	v_bfe_u32 v71, v70, 16, 1
	v_or_b32_e32 v116, 17, v38
	v_add3_u32 v115, v70, v71, s43
	v_lshlrev_b32_e32 v70, 12, v116
	v_mov_b32_e32 v71, v211
	v_lshl_add_u64 v[70:71], v[2:3], 0, v[70:71]
	global_load_dword v117, v[70:71], off
	v_or_b32_e32 v171, 19, v38
	global_store_short_d16_hi v[54:55], v115, off offset:448
	global_load_dword v115, v[70:71], off offset:128
	s_nop 0
	global_load_dword v118, v[70:71], off offset:256
	global_load_dword v119, v[70:71], off offset:384
	global_load_dword v129, v[70:71], off offset:512
	global_load_dword v161, v[70:71], off offset:640
	global_load_dword v162, v[70:71], off offset:768
	s_nop 0
	global_load_dword v70, v[70:71], off offset:896
	v_or_b32_e32 v71, 18, v38
	v_lshlrev_b32_e32 v54, 12, v71
	v_mov_b32_e32 v55, v211
	v_lshl_add_u64 v[54:55], v[2:3], 0, v[54:55]
	global_load_dword v163, v[54:55], off
	global_load_dword v164, v[54:55], off offset:128
	global_load_dword v165, v[54:55], off offset:256
	global_load_dword v166, v[54:55], off offset:384
	global_load_dword v167, v[54:55], off offset:512
	global_load_dword v168, v[54:55], off offset:640
	global_load_dword v169, v[54:55], off offset:768
	global_load_dword v170, v[54:55], off offset:896
	v_lshlrev_b32_e32 v54, 12, v171
	v_mov_b32_e32 v55, v211
	v_lshl_add_u64 v[54:55], v[2:3], 0, v[54:55]
	global_load_dword v172, v[54:55], off
	global_load_dword v173, v[54:55], off offset:128
	global_load_dword v174, v[54:55], off offset:256
	global_load_dword v175, v[54:55], off offset:384
	global_load_dword v176, v[54:55], off offset:512
	global_load_dword v177, v[54:55], off offset:640
	global_load_dword v178, v[54:55], off offset:768
	global_load_dword v179, v[54:55], off offset:896
	v_lshlrev_b32_e32 v54, 11, v39
	v_mul_f32_e32 v39, v8, v137
	v_mov_b32_e32 v55, v211
	v_lshl_add_u64 v[54:55], v[0:1], 0, v[54:55]
	s_waitcnt vmcnt(39)
	v_fma_f32 v39, -v209, v39, v84
	v_bfe_u32 v84, v39, 16, 1
	v_add3_u32 v39, v39, v84, s43
	global_store_short_d16_hi v[54:55], v39, off
	v_mul_f32_e32 v39, v120, v137
	s_waitcnt vmcnt(38)
	v_fma_f32 v39, -v209, v39, v85
	v_bfe_u32 v84, v39, 16, 1
	v_add3_u32 v39, v39, v84, s43
	global_store_short_d16_hi v[54:55], v39, off offset:64
	v_mul_f32_e32 v39, v104, v137
	s_waitcnt vmcnt(37)
	v_fma_f32 v39, -v209, v39, v86
	v_bfe_u32 v84, v39, 16, 1
	v_add3_u32 v39, v39, v84, s43
	global_store_short_d16_hi v[54:55], v39, off offset:128
	v_mul_f32_e32 v39, v88, v137
	s_waitcnt vmcnt(36)
	v_fma_f32 v39, -v209, v39, v87
	v_bfe_u32 v84, v39, 16, 1
	v_add3_u32 v39, v39, v84, s43
	global_store_short_d16_hi v[54:55], v39, off offset:192
	v_mul_f32_e32 v39, v72, v137
	s_waitcnt vmcnt(35)
	v_fma_f32 v39, -v209, v39, v100
	v_bfe_u32 v84, v39, 16, 1
	v_add3_u32 v39, v39, v84, s43
	global_store_short_d16_hi v[54:55], v39, off offset:256
	v_mul_f32_e32 v39, v56, v137
	s_waitcnt vmcnt(34)
	v_fma_f32 v39, -v209, v39, v101
	v_bfe_u32 v84, v39, 16, 1
	v_add3_u32 v39, v39, v84, s43
	global_store_short_d16_hi v[54:55], v39, off offset:320
	v_mul_f32_e32 v39, v40, v137
	s_waitcnt vmcnt(33)
	v_fma_f32 v39, -v209, v39, v102
	v_bfe_u32 v84, v39, 16, 1
	v_add3_u32 v39, v39, v84, s43
	global_store_short_d16_hi v[54:55], v39, off offset:384
	v_mul_f32_e32 v39, v24, v137
	s_waitcnt vmcnt(32)
	v_fma_f32 v39, -v209, v39, v103
	v_bfe_u32 v84, v39, 16, 1
	v_add3_u32 v39, v39, v84, s43
	global_store_short_d16_hi v[54:55], v39, off offset:448
	v_mul_f32_e32 v39, v9, v136
	v_lshlrev_b32_e32 v54, 11, v116
	v_mov_b32_e32 v55, v211
	v_lshl_add_u64 v[54:55], v[0:1], 0, v[54:55]
	s_waitcnt vmcnt(32)
	v_fma_f32 v39, -v209, v39, v117
	v_bfe_u32 v84, v39, 16, 1
	v_add3_u32 v39, v39, v84, s43
	global_store_short_d16_hi v[54:55], v39, off
	v_mul_f32_e32 v39, v121, v136
	s_waitcnt vmcnt(31)
	v_fma_f32 v39, -v209, v39, v115
	v_bfe_u32 v84, v39, 16, 1
	v_add3_u32 v39, v39, v84, s43
	global_store_short_d16_hi v[54:55], v39, off offset:64
	v_mul_f32_e32 v39, v105, v136
	s_waitcnt vmcnt(31)
	v_fma_f32 v39, -v209, v39, v118
	v_bfe_u32 v84, v39, 16, 1
	v_add3_u32 v39, v39, v84, s43
	global_store_short_d16_hi v[54:55], v39, off offset:128
	v_mul_f32_e32 v39, v89, v136
	s_waitcnt vmcnt(31)
	v_fma_f32 v39, -v209, v39, v119
	v_bfe_u32 v84, v39, 16, 1
	v_add3_u32 v39, v39, v84, s43
	global_store_short_d16_hi v[54:55], v39, off offset:192
	v_mul_f32_e32 v39, v73, v136
	s_waitcnt vmcnt(31)
	v_fma_f32 v39, -v209, v39, v129
	v_bfe_u32 v84, v39, 16, 1
	v_add3_u32 v39, v39, v84, s43
	global_store_short_d16_hi v[54:55], v39, off offset:256
	v_mul_f32_e32 v39, v57, v136
	s_waitcnt vmcnt(31)
	v_fma_f32 v39, -v209, v39, v161
	v_bfe_u32 v84, v39, 16, 1
	v_add3_u32 v39, v39, v84, s43
	global_store_short_d16_hi v[54:55], v39, off offset:320
	v_mul_f32_e32 v39, v41, v136
	s_waitcnt vmcnt(31)
	v_fma_f32 v39, -v209, v39, v162
	v_bfe_u32 v84, v39, 16, 1
	v_add3_u32 v39, v39, v84, s43
	global_store_short_d16_hi v[54:55], v39, off offset:384
	v_mul_f32_e32 v39, v25, v136
	s_waitcnt vmcnt(31)
	v_fma_f32 v39, -v209, v39, v70
	v_bfe_u32 v70, v39, 16, 1
	v_add3_u32 v39, v39, v70, s43
	global_store_short_d16_hi v[54:55], v39, off offset:448
	v_mul_f32_e32 v39, v10, v135
	s_waitcnt vmcnt(31)
	v_fma_f32 v39, -v209, v39, v163
	v_lshlrev_b32_e32 v54, 11, v71
	v_mov_b32_e32 v55, v211
	v_bfe_u32 v70, v39, 16, 1
	v_lshl_add_u64 v[54:55], v[0:1], 0, v[54:55]
	v_add3_u32 v39, v39, v70, s43
	global_store_short_d16_hi v[54:55], v39, off
	v_mul_f32_e32 v39, v122, v135
	s_waitcnt vmcnt(31)
	v_fma_f32 v39, -v209, v39, v164
	v_bfe_u32 v70, v39, 16, 1
	v_add3_u32 v39, v39, v70, s43
	global_store_short_d16_hi v[54:55], v39, off offset:64
	v_mul_f32_e32 v39, v106, v135
	s_waitcnt vmcnt(31)
	v_fma_f32 v39, -v209, v39, v165
	v_bfe_u32 v70, v39, 16, 1
	v_add3_u32 v39, v39, v70, s43
	global_store_short_d16_hi v[54:55], v39, off offset:128
	v_mul_f32_e32 v39, v90, v135
	s_waitcnt vmcnt(31)
	v_fma_f32 v39, -v209, v39, v166
	v_bfe_u32 v70, v39, 16, 1
	v_add3_u32 v39, v39, v70, s43
	global_store_short_d16_hi v[54:55], v39, off offset:192
	v_mul_f32_e32 v39, v74, v135
	s_waitcnt vmcnt(31)
	v_fma_f32 v39, -v209, v39, v167
	v_bfe_u32 v70, v39, 16, 1
	v_add3_u32 v39, v39, v70, s43
	global_store_short_d16_hi v[54:55], v39, off offset:256
	v_mul_f32_e32 v39, v58, v135
	s_waitcnt vmcnt(31)
	v_fma_f32 v39, -v209, v39, v168
	v_bfe_u32 v70, v39, 16, 1
	v_add3_u32 v39, v39, v70, s43
	global_store_short_d16_hi v[54:55], v39, off offset:320
	v_mul_f32_e32 v39, v42, v135
	s_waitcnt vmcnt(31)
	v_fma_f32 v39, -v209, v39, v169
	v_bfe_u32 v70, v39, 16, 1
	v_add3_u32 v39, v39, v70, s43
	global_store_short_d16_hi v[54:55], v39, off offset:384
	v_mul_f32_e32 v39, v26, v135
	s_waitcnt vmcnt(31)
	v_fma_f32 v39, -v209, v39, v170
	v_bfe_u32 v70, v39, 16, 1
	v_add3_u32 v39, v39, v70, s43
	global_store_short_d16_hi v[54:55], v39, off offset:448
	v_mul_f32_e32 v39, v11, v134
	s_waitcnt vmcnt(31)
	v_fma_f32 v39, -v209, v39, v172
	v_bfe_u32 v70, v39, 16, 1
	v_or_b32_e32 v85, 24, v38
	v_add3_u32 v39, v39, v70, s43
	v_lshlrev_b32_e32 v70, 12, v85
	v_mov_b32_e32 v71, v211
	v_lshlrev_b32_e32 v54, 11, v171
	v_mov_b32_e32 v55, v211
	v_lshl_add_u64 v[70:71], v[2:3], 0, v[70:71]
	v_lshl_add_u64 v[54:55], v[0:1], 0, v[54:55]
	global_load_dword v86, v[70:71], off
	global_load_dword v103, v[70:71], off offset:640
	v_or_b32_e32 v116, 25, v38
	global_store_short_d16_hi v[54:55], v39, off
	v_mul_f32_e32 v39, v123, v134
	s_waitcnt vmcnt(33)
	v_fma_f32 v39, -v209, v39, v173
	v_bfe_u32 v84, v39, 16, 1
	v_add3_u32 v39, v39, v84, s43
	global_load_dword v84, v[70:71], off offset:128
	s_nop 0
	global_store_short_d16_hi v[54:55], v39, off offset:64
	v_mul_f32_e32 v39, v107, v134
	s_waitcnt vmcnt(34)
	v_fma_f32 v39, -v209, v39, v174
	v_bfe_u32 v87, v39, 16, 1
	v_add3_u32 v39, v39, v87, s43
	global_load_dword v87, v[70:71], off offset:256
	s_nop 0
	global_store_short_d16_hi v[54:55], v39, off offset:128
	v_mul_f32_e32 v39, v91, v134
	s_waitcnt vmcnt(35)
	v_fma_f32 v39, -v209, v39, v175
	v_bfe_u32 v100, v39, 16, 1
	v_add3_u32 v39, v39, v100, s43
	global_load_dword v100, v[70:71], off offset:384
	s_nop 0
	global_store_short_d16_hi v[54:55], v39, off offset:192
	v_mul_f32_e32 v39, v75, v134
	s_waitcnt vmcnt(36)
	v_fma_f32 v39, -v209, v39, v176
	v_bfe_u32 v101, v39, 16, 1
	v_add3_u32 v39, v39, v101, s43
	global_load_dword v101, v[70:71], off offset:512
	s_nop 0
	global_store_short_d16_hi v[54:55], v39, off offset:256
	v_mul_f32_e32 v39, v59, v134
	s_waitcnt vmcnt(37)
	v_fma_f32 v39, -v209, v39, v177
	v_bfe_u32 v102, v39, 16, 1
	v_add3_u32 v39, v39, v102, s43
	global_store_short_d16_hi v[54:55], v39, off offset:320
	v_mul_f32_e32 v39, v43, v134
	s_waitcnt vmcnt(37)
	v_fma_f32 v39, -v209, v39, v178
	global_load_dword v102, v[70:71], off offset:768
	v_bfe_u32 v115, v39, 16, 1
	v_add3_u32 v39, v39, v115, s43
	global_store_short_d16_hi v[54:55], v39, off offset:384
	v_mul_f32_e32 v39, v27, v134
	global_load_dword v115, v[70:71], off offset:896
	s_waitcnt vmcnt(39)
	v_fma_f32 v39, -v209, v39, v179
	v_bfe_u32 v70, v39, 16, 1
	v_add3_u32 v39, v39, v70, s43
	v_lshlrev_b32_e32 v70, 12, v116
	v_mov_b32_e32 v71, v211
	v_lshl_add_u64 v[70:71], v[2:3], 0, v[70:71]
	global_load_dword v117, v[70:71], off
	s_nop 0
	global_store_short_d16_hi v[54:55], v39, off offset:448
	global_load_dword v118, v[70:71], off offset:128
	global_load_dword v119, v[70:71], off offset:256
	global_load_dword v129, v[70:71], off offset:384
	global_load_dword v161, v[70:71], off offset:512
	global_load_dword v162, v[70:71], off offset:640
	global_load_dword v163, v[70:71], off offset:768
	s_nop 0
	global_load_dword v70, v[70:71], off offset:896
	v_or_b32_e32 v71, 26, v38
	v_lshlrev_b32_e32 v54, 12, v71
	v_mov_b32_e32 v55, v211
	v_lshl_add_u64 v[54:55], v[2:3], 0, v[54:55]
	global_load_dword v164, v[54:55], off
	global_load_dword v165, v[54:55], off offset:128
	global_load_dword v166, v[54:55], off offset:256
	global_load_dword v167, v[54:55], off offset:384
	global_load_dword v168, v[54:55], off offset:512
	global_load_dword v169, v[54:55], off offset:640
	global_load_dword v170, v[54:55], off offset:768
	s_nop 0
	global_load_dword v54, v[54:55], off offset:896
	v_or_b32_e32 v55, 27, v38
	v_lshlrev_b32_e32 v38, 12, v55
	v_mov_b32_e32 v39, v211
	v_lshl_add_u64 v[2:3], v[2:3], 0, v[38:39]
	global_load_dword v38, v[2:3], off
	global_load_dword v39, v[2:3], off offset:128
	global_load_dword v171, v[2:3], off offset:256
	global_load_dword v172, v[2:3], off offset:384
	global_load_dword v173, v[2:3], off offset:512
	global_load_dword v174, v[2:3], off offset:640
	global_load_dword v175, v[2:3], off offset:768
	global_load_dword v176, v[2:3], off offset:896
	v_lshlrev_b32_e32 v2, 11, v85
	v_mul_f32_e32 v85, v12, v133
	v_mov_b32_e32 v3, v211
	v_lshl_add_u64 v[2:3], v[0:1], 0, v[2:3]
	s_waitcnt vmcnt(39)
	v_fma_f32 v85, -v209, v85, v86
	v_bfe_u32 v86, v85, 16, 1
	v_add3_u32 v85, v85, v86, s43
	global_store_short_d16_hi v[2:3], v85, off
	v_mul_f32_e32 v85, v124, v133
	s_waitcnt vmcnt(37)
	v_fma_f32 v84, -v209, v85, v84
	v_bfe_u32 v85, v84, 16, 1
	v_add3_u32 v84, v84, v85, s43
	global_store_short_d16_hi v[2:3], v84, off offset:64
	v_mul_f32_e32 v84, v108, v133
	s_waitcnt vmcnt(36)
	v_fma_f32 v84, -v209, v84, v87
	v_bfe_u32 v85, v84, 16, 1
	v_add3_u32 v84, v84, v85, s43
	global_store_short_d16_hi v[2:3], v84, off offset:128
	v_mul_f32_e32 v84, v92, v133
	s_waitcnt vmcnt(35)
	v_fma_f32 v84, -v209, v84, v100
	v_bfe_u32 v85, v84, 16, 1
	v_add3_u32 v84, v84, v85, s43
	global_store_short_d16_hi v[2:3], v84, off offset:192
	v_mul_f32_e32 v84, v76, v133
	s_waitcnt vmcnt(34)
	v_fma_f32 v84, -v209, v84, v101
	v_bfe_u32 v85, v84, 16, 1
	v_add3_u32 v84, v84, v85, s43
	global_store_short_d16_hi v[2:3], v84, off offset:256
	v_mul_f32_e32 v84, v60, v133
	v_fma_f32 v84, -v209, v84, v103
	v_bfe_u32 v85, v84, 16, 1
	v_add3_u32 v84, v84, v85, s43
	global_store_short_d16_hi v[2:3], v84, off offset:320
	v_mul_f32_e32 v84, v44, v133
	s_waitcnt vmcnt(33)
	v_fma_f32 v84, -v209, v84, v102
	v_bfe_u32 v85, v84, 16, 1
	v_add3_u32 v84, v84, v85, s43
	global_store_short_d16_hi v[2:3], v84, off offset:384
	v_mul_f32_e32 v84, v28, v133
	s_waitcnt vmcnt(32)
	v_fma_f32 v84, -v209, v84, v115
	v_bfe_u32 v85, v84, 16, 1
	v_add3_u32 v84, v84, v85, s43
	global_store_short_d16_hi v[2:3], v84, off offset:448
	v_mul_f32_e32 v84, v13, v132
	v_lshlrev_b32_e32 v2, 11, v116
	v_mov_b32_e32 v3, v211
	s_waitcnt vmcnt(32)
	v_fma_f32 v84, -v209, v84, v117
	v_bfe_u32 v85, v84, 16, 1
	v_lshl_add_u64 v[2:3], v[0:1], 0, v[2:3]
	v_add3_u32 v84, v84, v85, s43
	global_store_short_d16_hi v[2:3], v84, off
	v_mul_f32_e32 v84, v125, v132
	s_waitcnt vmcnt(31)
	v_fma_f32 v84, -v209, v84, v118
	v_bfe_u32 v85, v84, 16, 1
	v_add3_u32 v84, v84, v85, s43
	global_store_short_d16_hi v[2:3], v84, off offset:64
	v_mul_f32_e32 v84, v109, v132
	s_waitcnt vmcnt(31)
	v_fma_f32 v84, -v209, v84, v119
	v_bfe_u32 v85, v84, 16, 1
	v_add3_u32 v84, v84, v85, s43
	global_store_short_d16_hi v[2:3], v84, off offset:128
	v_mul_f32_e32 v84, v93, v132
	s_waitcnt vmcnt(31)
	v_fma_f32 v84, -v209, v84, v129
	v_bfe_u32 v85, v84, 16, 1
	v_add3_u32 v84, v84, v85, s43
	global_store_short_d16_hi v[2:3], v84, off offset:192
	v_mul_f32_e32 v84, v77, v132
	s_waitcnt vmcnt(31)
	v_fma_f32 v84, -v209, v84, v161
	v_bfe_u32 v85, v84, 16, 1
	v_add3_u32 v84, v84, v85, s43
	global_store_short_d16_hi v[2:3], v84, off offset:256
	v_mul_f32_e32 v84, v61, v132
	s_waitcnt vmcnt(31)
	v_fma_f32 v84, -v209, v84, v162
	v_bfe_u32 v85, v84, 16, 1
	v_add3_u32 v84, v84, v85, s43
	global_store_short_d16_hi v[2:3], v84, off offset:320
	v_mul_f32_e32 v84, v45, v132
	s_waitcnt vmcnt(31)
	v_fma_f32 v84, -v209, v84, v163
	v_bfe_u32 v85, v84, 16, 1
	v_add3_u32 v84, v84, v85, s43
	global_store_short_d16_hi v[2:3], v84, off offset:384
	v_mul_f32_e32 v84, v29, v132
	s_waitcnt vmcnt(31)
	v_fma_f32 v70, -v209, v84, v70
	v_bfe_u32 v84, v70, 16, 1
	v_add3_u32 v70, v70, v84, s43
	global_store_short_d16_hi v[2:3], v70, off offset:448
	v_mul_f32_e32 v70, v14, v131
	s_waitcnt vmcnt(31)
	v_fma_f32 v70, -v209, v70, v164
	v_lshlrev_b32_e32 v2, 11, v71
	v_mov_b32_e32 v3, v211
	v_bfe_u32 v71, v70, 16, 1
	v_lshl_add_u64 v[2:3], v[0:1], 0, v[2:3]
	v_add3_u32 v70, v70, v71, s43
	global_store_short_d16_hi v[2:3], v70, off
	v_mul_f32_e32 v70, v126, v131
	s_waitcnt vmcnt(31)
	v_fma_f32 v70, -v209, v70, v165
	v_bfe_u32 v71, v70, 16, 1
	v_add3_u32 v70, v70, v71, s43
	global_store_short_d16_hi v[2:3], v70, off offset:64
	v_mul_f32_e32 v70, v110, v131
	s_waitcnt vmcnt(31)
	v_fma_f32 v70, -v209, v70, v166
	v_bfe_u32 v71, v70, 16, 1
	v_add3_u32 v70, v70, v71, s43
	global_store_short_d16_hi v[2:3], v70, off offset:128
	v_mul_f32_e32 v70, v94, v131
	s_waitcnt vmcnt(31)
	v_fma_f32 v70, -v209, v70, v167
	v_bfe_u32 v71, v70, 16, 1
	v_add3_u32 v70, v70, v71, s43
	global_store_short_d16_hi v[2:3], v70, off offset:192
	v_mul_f32_e32 v70, v78, v131
	s_waitcnt vmcnt(31)
	v_fma_f32 v70, -v209, v70, v168
	v_bfe_u32 v71, v70, 16, 1
	v_add3_u32 v70, v70, v71, s43
	global_store_short_d16_hi v[2:3], v70, off offset:256
	v_mul_f32_e32 v70, v62, v131
	s_waitcnt vmcnt(31)
	v_fma_f32 v70, -v209, v70, v169
	v_bfe_u32 v71, v70, 16, 1
	v_add3_u32 v70, v70, v71, s43
	global_store_short_d16_hi v[2:3], v70, off offset:320
	v_mul_f32_e32 v70, v46, v131
	s_waitcnt vmcnt(31)
	v_fma_f32 v70, -v209, v70, v170
	v_bfe_u32 v71, v70, 16, 1
	v_add3_u32 v70, v70, v71, s43
	global_store_short_d16_hi v[2:3], v70, off offset:384
	v_mul_f32_e32 v70, v30, v131
	s_waitcnt vmcnt(31)
	v_fma_f32 v54, -v209, v70, v54
	v_bfe_u32 v70, v54, 16, 1
	v_add3_u32 v54, v54, v70, s43
	global_store_short_d16_hi v[2:3], v54, off offset:448
	v_lshlrev_b32_e32 v2, 11, v55
	v_mov_b32_e32 v3, v211
	v_lshl_add_u64 v[0:1], v[0:1], 0, v[2:3]
	v_mul_f32_e32 v2, v15, v130
	s_waitcnt vmcnt(31)
	v_fma_f32 v2, -v209, v2, v38
	v_bfe_u32 v3, v2, 16, 1
	v_add3_u32 v2, v2, v3, s43
	global_store_short_d16_hi v[0:1], v2, off
	v_mul_f32_e32 v2, v127, v130
	s_waitcnt vmcnt(31)
	v_fma_f32 v2, -v209, v2, v39
	v_bfe_u32 v3, v2, 16, 1
	v_add3_u32 v2, v2, v3, s43
	global_store_short_d16_hi v[0:1], v2, off offset:64
	v_mul_f32_e32 v2, v111, v130
	s_waitcnt vmcnt(31)
	v_fma_f32 v2, -v209, v2, v171
	v_bfe_u32 v3, v2, 16, 1
	v_add3_u32 v2, v2, v3, s43
	global_store_short_d16_hi v[0:1], v2, off offset:128
	v_mul_f32_e32 v2, v95, v130
	s_waitcnt vmcnt(31)
	v_fma_f32 v2, -v209, v2, v172
	v_bfe_u32 v3, v2, 16, 1
	v_add3_u32 v2, v2, v3, s43
	global_store_short_d16_hi v[0:1], v2, off offset:192
	v_mul_f32_e32 v2, v79, v130
	s_waitcnt vmcnt(31)
	v_fma_f32 v2, -v209, v2, v173
	v_bfe_u32 v3, v2, 16, 1
	v_add3_u32 v2, v2, v3, s43
	global_store_short_d16_hi v[0:1], v2, off offset:256
	v_mul_f32_e32 v2, v63, v130
	s_waitcnt vmcnt(31)
	v_fma_f32 v2, -v209, v2, v174
	v_bfe_u32 v3, v2, 16, 1
	v_add3_u32 v2, v2, v3, s43
	global_store_short_d16_hi v[0:1], v2, off offset:320
	v_mul_f32_e32 v2, v47, v130
	s_waitcnt vmcnt(31)
	v_fma_f32 v2, -v209, v2, v175
	v_bfe_u32 v3, v2, 16, 1
	v_add3_u32 v2, v2, v3, s43
	global_store_short_d16_hi v[0:1], v2, off offset:384
	v_mul_f32_e32 v2, v31, v130
	s_waitcnt vmcnt(31)
	v_fma_f32 v2, -v209, v2, v176
	v_bfe_u32 v3, v2, 16, 1
	v_add3_u32 v2, v2, v3, s43
	global_store_short_d16_hi v[0:1], v2, off offset:448
